# latent attention loops: per-segment s_setprio flips removed, waves 4-7 at static s_setprio 1 for the whole loop
# baseline (speedup 1.0000x reference)
; __device__ __forceinline__ int opaque_tid() { int t = threadIdx.x; asm volatile("" : "+v"(t)); return t; }
; #define AT_LOAD(t_) do { const bf16_t* kn = ksrc + (size_t)(t_) * AKT * INW; const bf16_t* vn = vsrc + (t_) * AKT; \
;         kreg0 = *(const u32x4*)kn; kreg1 = *(const u32x4*)(kn + (size_t)64 * INW); vreg0 = *(const u32x4*)vn; vreg1 = *(const u32x4*)(vn + 64); } while (0)
; template <int DK, bool IS_A>
; __device__ __forceinline__ void attn_unit(const Params& P, int l, LAS unsigned char* lds, int b, int grp, int qtok0, int nkeys) {
;     const int tid = opaque_tid(), lane = tid & 63, wave = tid >> 6, s = wave >> 2, wq = wave & 3, r32 = lane & 31, hi = lane >> 5;
;     const bf16_t* proj = (const bf16_t*)(P.ws + WS_PROJ);
;     bf16_t* mix = (bf16_t*)(P.ws + WS_H);
;     const int qcol = IS_A ? PA_Q + grp * 64 + s * 32 : PC_Q + (2 * grp + s) * 64;
;     const int kcol = IS_A ? PA_K + grp * 64 : PC_K + grp * 64;
;     const int koff = IS_A ? s * 32 : 0;
;     const bf16_t* VT = IS_A ? (const bf16_t*)(P.ws + WS_VTA) + ((size_t)(b * 4 + grp) * 64) * TT : (const bf16_t*)(P.ws + WS_VTC) + ((size_t)(b * 2 + grp) * 64) * TT;
;     const size_t qrow = (size_t)b * TT + qtok0 + wq * 64 + r32;
;     bf16x8 qa[DK / 16], qb[DK / 16];
; #pragma unroll
;     for (int i = 0; i < DK / 16; ++i) { qa[i] = *(const bf16x8*)(proj + qrow * INW + qcol + i * 16 + hi * 8); qb[i] = *(const bf16x8*)(proj + (qrow + 32) * INW + qcol + i * 16 + hi * 8); }
;     const int lrow = tid >> 3, lch = tid & 7;
;     const bf16_t* ksrc = proj + ((size_t)b * TT + lrow) * INW + kcol + lch * 8;
;     const bf16_t* vsrc = VT + (size_t)lrow * TT + lch * 8;
;     const int NT = nkeys / AKT;
;     u32x4 kreg0, kreg1, vreg0, vreg1;
;     ...
;     const int kfo = r32 * AK_PITCH + (koff + 8 * hi) * 2, vfo = AK_BYTES + r32 * AV_PITCH + 8 * hi;
;     AT_LOAD(0); AT_STORE(0);
;     __syncthreads();
;     float ma = -1e30f, mb = -1e30f, la = 0.f, lb_ = 0.f;
;     f32x16 oa0, oa1, ob0, ob1;
; #pragma unroll
;     for (int r = 0; r < 16; ++r) { oa0[r] = 0.f; oa1[r] = 0.f; ob0[r] = 0.f; ob1[r] = 0.f; }
.LBB0_415:
	s_andn2_b64 vcc, exec, s[10:11]
	s_cbranch_vccnz .LBB0_439
	s_add_i32 s8, s37, 0xfffffe60
	s_lshr_b32 s15, s8, 5
	s_lshl_b32 s8, s37, 8
	s_and_b32 s8, s8, 0x700
	s_mul_i32 s10, s15, 0x900
	s_add_i32 s9, s8, s10
	s_lshl_b32 s8, s37, 3
	v_mov_b32_e32 v165, v200
	s_and_b32 s8, s8, 0xc0
	s_lshl_b32 s11, s15, 8
	s_or_b32 s11, s11, s8
	v_ashrrev_i32_e32 v2, 3, v165
	s_mul_i32 s64, s11, 0x900
	s_mov_b32 s11, s65
	v_ashrrev_i32_e32 v3, 31, v2
	s_addk_i32 s9, 0x100
	v_mov_b64_e32 v[0:1], s[56:57]
	s_lshl_b64 s[12:13], s[64:65], 1
	v_readlane_b32 s7, v255, 8
	v_lshl_add_u64 v[4:5], v[2:3], 0, s[10:11]
	s_add_u32 s12, s7, s12
	v_readlane_b32 s7, v255, 9
	v_mad_u64_u32 v[6:7], s[10:11], v4, s23, v[0:1]
	s_addc_u32 s13, s7, s13
	v_mad_i32_i24 v7, v5, s23, v7
	s_lshl_b32 s64, s8, 1
	v_lshlrev_b32_e32 v3, 4, v165
	v_lshl_add_u64 v[6:7], v[6:7], 0, s[64:65]
	v_and_b32_e32 v166, 0x70, v3
	v_mov_b32_e32 v167, v129
	v_lshl_add_u64 v[6:7], v[6:7], 0, v[166:167]
	s_mov_b32 s7, 0x58000
	v_mov_b64_e32 v[8:9], s[12:13]
	global_load_dwordx4 v[130:133], v[6:7], off offset:512
	v_add_co_u32_e32 v6, vcc, s7, v6
	v_mad_i64_i32 v[8:9], s[10:11], v2, s27, v[8:9]
	s_nop 0
	v_addc_co_u32_e32 v7, vcc, 0, v7, vcc
	v_lshl_add_u64 v[8:9], v[8:9], 0, v[166:167]
	global_load_dwordx4 v[134:137], v[6:7], off offset:512
	global_load_dwordx4 v[154:157], v[8:9], off
	global_load_dwordx4 v[158:161], v[8:9], off offset:128
	v_ashrrev_i32_e32 v172, 8, v165
	v_and_b32_e32 v173, 0xc0, v165
	v_and_b32_e32 v3, 31, v165
	v_lshlrev_b32_e32 v11, 5, v172
	v_add_u32_e32 v6, s8, v11
	v_or3_b32 v128, s9, v173, v3
	v_bfe_u32 v10, v165, 5, 1
	v_mad_u64_u32 v[0:1], s[10:11], v128, s23, v[0:1]
	v_ashrrev_i32_e32 v7, 31, v6
	v_lshl_add_u64 v[0:1], v[6:7], 1, v[0:1]
	v_lshlrev_b32_e32 v162, 4, v10
	v_mov_b32_e32 v163, v129
	v_lshl_add_u64 v[0:1], v[0:1], 0, v[162:163]
	s_mov_b32 s7, 0x2c000
	s_mov_b64 s[10:11], 0x2c000
	v_add_co_u32_e32 v8, vcc, s7, v0
	v_lshl_add_u64 v[6:7], v[0:1], 0, s[10:11]
	s_nop 0
	v_addc_co_u32_e32 v9, vcc, 0, v1, vcc
	global_load_dwordx4 v[138:141], v[0:1], off
	global_load_dwordx4 v[142:145], v[0:1], off offset:32
	global_load_dwordx4 v[146:149], v[8:9], off
	global_load_dwordx4 v[150:153], v[6:7], off offset:32
	s_movk_i32 s7, 0x90
	v_and_b32_e32 v0, 63, v165
	v_lshlrev_b32_e32 v164, 3, v10
	v_mul_lo_u32 v175, v2, s7
	s_movk_i32 s7, 0x108
	v_mul_lo_u32 v176, v2, s7
	v_lshlrev_b32_e32 v174, 2, v0
	v_or_b32_e32 v1, v164, v11
	v_add3_u32 v0, 0, v175, v166
	s_movk_i32 s7, 0x78
	v_mad_u64_u32 v[6:7], s[10:11], v2, s7, v[0:1]
	s_bfe_u32 s13, s37, 0x20003
	s_mul_i32 s12, s15, 0x90000
	s_mul_i32 s10, s13, 0x24000
	s_add_i32 s64, s12, s10
	s_lshl_b64 s[10:11], s[64:65], 1
	s_add_u32 s10, s54, s10
	v_lshlrev_b32_e32 v179, 1, v1
	v_add_u32_e32 v1, 0x4800, v6
	s_addc_u32 s11, s55, s11
	v_mul_u32_u24_e32 v177, 0x90, v3
	s_waitcnt vmcnt(13)
	v_mul_u32_u24_e32 v178, 0x108, v3
	v_add_u32_e32 v3, 0x4880, v6
	v_mov_b32_e32 v14, v129
	v_mov_b32_e32 v15, v129
	v_mov_b32_e32 v6, v129
	v_mov_b32_e32 v7, v129
	s_waitcnt vmcnt(7)
	ds_write_b128 v0, v[130:133]
	s_waitcnt vmcnt(6)
	ds_write_b128 v0, v[134:137] offset:9216
	s_waitcnt vmcnt(5)
	ds_write2_b64 v1, v[154:155], v[156:157] offset1:1
	s_waitcnt vmcnt(4)
	ds_write2_b64 v3, v[158:159], v[160:161] offset1:1
	v_mov_b64_e32 v[0:1], s[10:11]
	v_mad_i64_i32 v[168:169], s[10:11], v2, s27, v[0:1]
	s_lshl_b32 s10, s13, 7
	s_add_u32 s10, s54, s10
	s_addc_u32 s11, s55, 0
	v_mov_b64_e32 v[0:1], s[10:11]
	v_mad_u64_u32 v[170:171], s[10:11], v4, s23, v[0:1]
	v_mad_i32_i24 v171, v5, s23, v171
	v_mov_b32_e32 v0, v129
	v_mov_b32_e32 v1, v129
	v_mov_b32_e32 v2, v129
	v_mov_b32_e32 v3, v129
	v_mov_b32_e32 v4, v129
	v_mov_b32_e32 v5, v129
	v_mov_b32_e32 v8, v129
	v_mov_b32_e32 v9, v129
	v_mov_b32_e32 v10, v129
	v_mov_b32_e32 v11, v129
	v_mov_b32_e32 v12, v129
	v_mov_b32_e32 v13, v129
	v_mov_b64_e32 v[30:31], v[14:15]
	v_mov_b64_e32 v[46:47], v[14:15]
	v_mov_b64_e32 v[62:63], v[14:15]
	s_mov_b32 s9, 0
	v_xor_b32_e32 v163, 0x80, v174
	v_mov_b32_e32 v185, 0
	v_mov_b32_e32 v181, 0xf149f2ca
	v_mov_b32_e32 v184, 0xf149f2ca
	v_mov_b32_e32 v180, 0
	v_mov_b64_e32 v[28:29], v[12:13]
	v_mov_b64_e32 v[26:27], v[10:11]
	v_mov_b64_e32 v[24:25], v[8:9]
	v_mov_b64_e32 v[22:23], v[6:7]
	v_mov_b64_e32 v[20:21], v[4:5]
	v_mov_b64_e32 v[18:19], v[2:3]
	v_mov_b64_e32 v[16:17], v[0:1]
	v_mov_b64_e32 v[44:45], v[12:13]
	v_mov_b64_e32 v[42:43], v[10:11]
	v_mov_b64_e32 v[40:41], v[8:9]
	v_mov_b64_e32 v[38:39], v[6:7]
	v_mov_b64_e32 v[36:37], v[4:5]
	v_mov_b64_e32 v[34:35], v[2:3]
	v_mov_b64_e32 v[32:33], v[0:1]
	v_mov_b64_e32 v[60:61], v[12:13]
	v_mov_b64_e32 v[58:59], v[10:11]
	v_mov_b64_e32 v[56:57], v[8:9]
	v_mov_b64_e32 v[54:55], v[6:7]
	v_mov_b64_e32 v[52:53], v[4:5]
	v_mov_b64_e32 v[50:51], v[2:3]
	v_mov_b64_e32 v[48:49], v[0:1]
	s_waitcnt lgkmcnt(0)
	s_waitcnt vmcnt(0)
	s_mov_b32 s100, 0
	v_readfirstlane_b32 s101, v200
	s_nop 3
	s_lshr_b32 s101, s101, 8
	s_cmp_eq_u32 s101, 0
	s_cbranch_scc1 .Lsp_a
	s_setprio 1
.Lsp_a:
	s_barrier
	s_branch .LBB0_418

; #define LAS __attribute__((address_space(3)))
; template <int DK, bool IS_A>
; __device__ __forceinline__ void attn_unit(const Params& P, int l, LAS unsigned char* lds, int b, int grp, int qtok0, int nkeys) {
;     ...
;         for (int h = 0; h < 2; ++h) {
;             const LAS unsigned char* kb = lds + buf * A_BUF + kfo + h * 64 * AK_PITCH;
;             const LAS unsigned char* vb = lds + buf * A_BUF + vfo + h * 128;
;             f32x16 pa[2], pb[2];
; #pragma unroll
;             for (int jj = 0; jj < 2; ++jj)
; #pragma unroll
;                 for (int r = 0; r < 16; ++r) { pa[jj][r] = 0.f; pb[jj][r] = 0.f; }
;             __builtin_amdgcn_s_setprio(1);
; #pragma unroll
;             for (int i = 0; i < DK / 16; ++i)
; #pragma unroll
;                 for (int jj = 0; jj < 2; ++jj) {
;                     const bf16x8 kf = *(const LAS bf16x8*)(kb + jj * 32 * AK_PITCH + i * 32);
;                     pa[jj] = __builtin_amdgcn_mfma_f32_32x32x16_bf16(kf, qa[i], pa[jj], 0, 0, 0);
;                     pb[jj] = __builtin_amdgcn_mfma_f32_32x32x16_bf16(kf, qb[i], pb[jj], 0, 0, 0);
;                 }
;             __builtin_amdgcn_s_setprio(0);
.LBB0_420:
	s_mov_b32 s12, s100
	v_add_u32_e32 v64, s12, v177
	v_add_u32_e32 v187, v64, v179
	ds_read_b128 v[64:67], v187
	ds_read_b128 v[188:191], v187 offset:32
	s_waitcnt lgkmcnt(1)
	v_mfma_f32_32x32x16_bf16 v[112:127], v[64:67], v[138:141], 0
	v_mfma_f32_32x32x16_bf16 v[96:111], v[64:67], v[146:149], 0
	ds_read_b128 v[64:67], v187 offset:4608
	s_waitcnt lgkmcnt(1)
	v_mfma_f32_32x32x16_bf16 v[112:127], v[188:191], v[142:145], v[112:127]
	v_mfma_f32_32x32x16_bf16 v[96:111], v[188:191], v[150:153], v[96:111]
	ds_read_b128 v[188:191], v187 offset:4640
	s_waitcnt lgkmcnt(1)
	v_mfma_f32_32x32x16_bf16 v[80:95], v[64:67], v[138:141], 0
	v_mfma_f32_32x32x16_bf16 v[64:79], v[64:67], v[146:149], 0
	s_waitcnt lgkmcnt(0)
	v_mfma_f32_32x32x16_bf16 v[80:95], v[188:191], v[142:145], v[80:95]
	v_mfma_f32_32x32x16_bf16 v[64:79], v[188:191], v[150:153], v[64:79]
	s_nop 9
	v_max_f32_e32 v182, v80, v80
	v_max_f32_e32 v183, v112, v112
	v_max_f32_e32 v182, v183, v182
	v_max3_f32 v183, v81, v114, v82
	v_max3_f32 v182, v182, v113, v115
	v_max3_f32 v183, v183, v116, v84
	v_max3_f32 v182, v182, v83, v117
	v_max3_f32 v183, v183, v118, v86
	v_max3_f32 v182, v182, v85, v119
	v_max3_f32 v183, v183, v120, v88
	v_max3_f32 v182, v182, v87, v121
	v_max3_f32 v183, v183, v122, v90
	v_max3_f32 v182, v182, v89, v123
	v_max3_f32 v183, v183, v124, v92
	v_max3_f32 v182, v182, v91, v125
	v_max3_f32 v183, v183, v126, v94
	v_max3_f32 v182, v182, v93, v127
	v_max3_f32 v182, v182, v95, v183
	ds_bpermute_b32 v183, v163, v182
	s_waitcnt lgkmcnt(0)
	v_max3_f32 v188, v181, v182, v183
	v_cmp_gt_f32_e32 vcc, v188, v181
	s_cbranch_vccz .LBB0_422
	v_sub_f32_e32 v181, v181, v188
	v_exp_f32_e32 v182, v181
	s_nop 0
	v_pk_mul_f32 v[62:63], v[62:63], v[182:183] op_sel_hi:[1,0]
	v_pk_mul_f32 v[60:61], v[60:61], v[182:183] op_sel_hi:[1,0]
	v_pk_mul_f32 v[58:59], v[58:59], v[182:183] op_sel_hi:[1,0]
	v_pk_mul_f32 v[56:57], v[56:57], v[182:183] op_sel_hi:[1,0]
	v_pk_mul_f32 v[54:55], v[54:55], v[182:183] op_sel_hi:[1,0]
	v_pk_mul_f32 v[52:53], v[52:53], v[182:183] op_sel_hi:[1,0]
	v_pk_mul_f32 v[50:51], v[50:51], v[182:183] op_sel_hi:[1,0]
	v_pk_mul_f32 v[48:49], v[48:49], v[182:183] op_sel_hi:[1,0]
	v_pk_mul_f32 v[46:47], v[46:47], v[182:183] op_sel_hi:[1,0]
	v_pk_mul_f32 v[44:45], v[44:45], v[182:183] op_sel_hi:[1,0]
	v_pk_mul_f32 v[42:43], v[42:43], v[182:183] op_sel_hi:[1,0]
	v_pk_mul_f32 v[40:41], v[40:41], v[182:183] op_sel_hi:[1,0]
	v_pk_mul_f32 v[38:39], v[38:39], v[182:183] op_sel_hi:[1,0]
	v_pk_mul_f32 v[36:37], v[36:37], v[182:183] op_sel_hi:[1,0]
	v_pk_mul_f32 v[34:35], v[34:35], v[182:183] op_sel_hi:[1,0]
	v_pk_mul_f32 v[32:33], v[32:33], v[182:183] op_sel_hi:[1,0]
	v_mul_f32_e32 v185, v185, v182
	s_branch .LBB0_423

; #define LAS __attribute__((address_space(3)))
; __device__ __forceinline__ unsigned pk2(float lo, float hi) { f32x2_t v = {lo, hi}; bf16x2_t b = __builtin_convertvector(v, bf16x2_t); return __builtin_bit_cast(unsigned, b); }
; template <int DK, bool IS_A>
; __device__ __forceinline__ void attn_unit(const Params& P, int l, LAS unsigned char* lds, int b, int grp, int qtok0, int nkeys) {
;     ...
;             AT_SOFTMAX(pa, ma, la, oa0, oa1);
;             AT_SOFTMAX(pb, mb, lb_, ob0, ob1);
;     ...
; #pragma unroll
;             for (int ks = 0; ks < 4; ++ks) {
;                 const int o8 = 8 * (ks & 1);
;                 u32x4 w; const f32x16& xa = pa[ks >> 1]; const f32x16& xb = pb[ks >> 1];
;                 w.x = pk2(xa[o8], xa[o8 + 1]); w.y = pk2(xa[o8 + 2], xa[o8 + 3]); w.z = pk2(xa[o8 + 4], xa[o8 + 5]); w.w = pk2(xa[o8 + 6], xa[o8 + 7]);
;                 const bf16x8 pfa = __builtin_bit_cast(bf16x8, w);
;                 w.x = pk2(xb[o8], xb[o8 + 1]); w.y = pk2(xb[o8 + 2], xb[o8 + 3]); w.z = pk2(xb[o8 + 4], xb[o8 + 5]); w.w = pk2(xb[o8 + 6], xb[o8 + 7]);
;                 const bf16x8 pfb = __builtin_bit_cast(bf16x8, w);
;                 const u32x2 a0 = *(const LAS u32x2*)(vb + ks * 32), a1 = *(const LAS u32x2*)(vb + ks * 32 + 16);
;                 const u32x2 c0 = *(const LAS u32x2*)(vb + 32 * AV_PITCH + ks * 32), c1 = *(const LAS u32x2*)(vb + 32 * AV_PITCH + ks * 32 + 16);
;                 const bf16x8 v0 = __builtin_bit_cast(bf16x8, ((u32x4){a0.x, a0.y, a1.x, a1.y})), v1 = __builtin_bit_cast(bf16x8, ((u32x4){c0.x, c0.y, c1.x, c1.y}));
;                 oa0 = __builtin_amdgcn_mfma_f32_32x32x16_bf16(v0, pfa, oa0, 0, 0, 0);
;                 oa1 = __builtin_amdgcn_mfma_f32_32x32x16_bf16(v1, pfa, oa1, 0, 0, 0);
;                 ob0 = __builtin_amdgcn_mfma_f32_32x32x16_bf16(v0, pfb, ob0, 0, 0, 0);
;                 ob1 = __builtin_amdgcn_mfma_f32_32x32x16_bf16(v1, pfb, ob1, 0, 0, 0);
;             }
.LBB0_426:
	v_sub_f32_e32 v112, v112, v188
	v_exp_f32_e32 v112, v112
	v_sub_f32_e32 v113, v113, v188
	v_exp_f32_e32 v113, v113
	v_sub_f32_e32 v114, v114, v188
	v_exp_f32_e32 v114, v114
	v_sub_f32_e32 v115, v115, v188
	v_exp_f32_e32 v115, v115
	v_sub_f32_e32 v116, v116, v188
	v_add_f32_e32 v181, 0, v112
	v_exp_f32_e32 v116, v116
	v_sub_f32_e32 v117, v117, v188
	v_add_f32_e32 v181, v113, v181
	v_exp_f32_e32 v117, v117
	v_sub_f32_e32 v118, v118, v188
	v_add_f32_e32 v181, v114, v181
	v_exp_f32_e32 v118, v118
	v_sub_f32_e32 v119, v119, v188
	v_add_f32_e32 v181, v115, v181
	v_exp_f32_e32 v119, v119
	v_sub_f32_e32 v120, v120, v188
	v_add_f32_e32 v181, v116, v181
	v_exp_f32_e32 v120, v120
	v_sub_f32_e32 v121, v121, v188
	v_add_f32_e32 v181, v117, v181
	v_exp_f32_e32 v121, v121
	v_sub_f32_e32 v122, v122, v188
	v_add_f32_e32 v181, v118, v181
	v_exp_f32_e32 v122, v122
	v_sub_f32_e32 v123, v123, v188
	v_add_f32_e32 v181, v119, v181
	v_exp_f32_e32 v123, v123
	v_sub_f32_e32 v124, v124, v188
	v_add_f32_e32 v181, v120, v181
	v_exp_f32_e32 v124, v124
	v_sub_f32_e32 v125, v125, v188
	v_add_f32_e32 v181, v121, v181
	v_exp_f32_e32 v125, v125
	v_sub_f32_e32 v126, v126, v188
	v_add_f32_e32 v181, v122, v181
	v_exp_f32_e32 v126, v126
	v_sub_f32_e32 v127, v127, v188
	v_add_f32_e32 v181, v123, v181
	v_exp_f32_e32 v127, v127
	v_sub_f32_e32 v80, v80, v188
	v_add_f32_e32 v181, v124, v181
	v_exp_f32_e32 v211, v80
	v_sub_f32_e32 v80, v81, v188
	v_add_f32_e32 v181, v125, v181
	v_exp_f32_e32 v212, v80
	v_sub_f32_e32 v81, v82, v188
	v_add_f32_e32 v80, v126, v181
	v_exp_f32_e32 v181, v81
	v_sub_f32_e32 v81, v83, v188
	v_add_f32_e32 v80, v127, v80
	v_exp_f32_e32 v213, v81
	v_sub_f32_e32 v81, v84, v188
	v_add_f32_e32 v80, v211, v80
	v_exp_f32_e32 v214, v81
	v_sub_f32_e32 v81, v85, v188
	v_add_f32_e32 v80, v212, v80
	v_exp_f32_e32 v215, v81
	v_sub_f32_e32 v81, v86, v188
	v_add_f32_e32 v80, v181, v80
	v_exp_f32_e32 v216, v81
	v_sub_f32_e32 v81, v87, v188
	v_add_f32_e32 v80, v213, v80
	v_exp_f32_e32 v217, v81
	v_sub_f32_e32 v81, v88, v188
	v_add_f32_e32 v80, v214, v80
	v_exp_f32_e32 v218, v81
	v_sub_f32_e32 v81, v89, v188
	v_add_f32_e32 v80, v215, v80
	v_exp_f32_e32 v220, v81
	v_add_f32_e32 v80, v216, v80
	v_add_f32_e32 v80, v217, v80
	v_add_f32_e32 v80, v218, v80
	v_add_f32_e32 v224, v220, v80
	v_sub_f32_e32 v80, v90, v188
	v_exp_f32_e32 v225, v80
	v_sub_f32_e32 v80, v91, v188
	v_exp_f32_e32 v226, v80
	v_sub_f32_e32 v80, v92, v188
	v_exp_f32_e32 v92, v80
	v_add_u32_e32 v80, s12, v178
	v_sub_f32_e32 v81, v96, v186
	v_add_u32_e32 v88, v80, v164
	v_exp_f32_e32 v184, v81
	v_sub_f32_e32 v81, v97, v186
	v_add_u32_e32 v182, 0x4800, v88
	v_add_u32_e32 v183, 0x6800, v88
	v_exp_f32_e32 v189, v81
	ds_read2_b64 v[80:83], v182 offset1:2
	ds_read2_b64 v[88:91], v183 offset0:32 offset1:34
	v_sub_f32_e32 v96, v99, v186
	v_sub_f32_e32 v84, v98, v186
	v_exp_f32_e32 v191, v96
	v_sub_f32_e32 v96, v100, v186
	v_exp_f32_e32 v190, v84
	v_cvt_pk_bf16_f32 v84, v112, v113
	v_cvt_pk_bf16_f32 v85, v114, v115
	v_cvt_pk_bf16_f32 v86, v116, v117
	v_cvt_pk_bf16_f32 v87, v118, v119
	v_exp_f32_e32 v192, v96
	v_sub_f32_e32 v96, v101, v186
	s_waitcnt lgkmcnt(1)
	v_mfma_f32_32x32x16_bf16 v[48:63], v[80:83], v[84:87], v[48:63]
	v_exp_f32_e32 v193, v96
	v_sub_f32_e32 v96, v102, v186
	v_exp_f32_e32 v194, v96
	v_sub_f32_e32 v96, v107, v186
	v_exp_f32_e32 v199, v96
	v_sub_f32_e32 v96, v108, v186
	v_exp_f32_e32 v204, v96
	s_waitcnt lgkmcnt(0)
	v_mfma_f32_32x32x16_bf16 v[32:47], v[88:91], v[84:87], v[32:47]
	v_sub_f32_e32 v84, v103, v186
	v_exp_f32_e32 v195, v84
	v_cvt_pk_bf16_f32 v84, v184, v189
	v_cvt_pk_bf16_f32 v85, v190, v191
	v_cvt_pk_bf16_f32 v86, v192, v193
	v_cvt_pk_bf16_f32 v87, v194, v195
	v_sub_f32_e32 v96, v109, v186
	v_exp_f32_e32 v205, v96
	v_mfma_f32_32x32x16_bf16 v[16:31], v[80:83], v[84:87], v[16:31]
	v_sub_f32_e32 v80, v93, v188
	v_exp_f32_e32 v93, v80
	v_sub_f32_e32 v80, v104, v186
	v_exp_f32_e32 v196, v80
	v_sub_f32_e32 v80, v105, v186
	v_exp_f32_e32 v197, v80
	ds_read2_b64 v[80:83], v182 offset0:4 offset1:6
	v_mfma_f32_32x32x16_bf16 v[0:15], v[88:91], v[84:87], v[0:15]
	ds_read2_b64 v[88:91], v183 offset0:36 offset1:38
	v_sub_f32_e32 v84, v106, v186
	v_exp_f32_e32 v198, v84
	v_cvt_pk_bf16_f32 v84, v120, v121
	v_cvt_pk_bf16_f32 v85, v122, v123
	v_cvt_pk_bf16_f32 v86, v124, v125
	v_cvt_pk_bf16_f32 v87, v126, v127
	v_sub_f32_e32 v96, v110, v186
	v_exp_f32_e32 v206, v96
	s_waitcnt lgkmcnt(1)
	v_mfma_f32_32x32x16_bf16 v[48:63], v[80:83], v[84:87], v[48:63]
	v_sub_f32_e32 v64, v64, v186
	v_exp_f32_e32 v208, v64
	v_sub_f32_e32 v64, v65, v186
	v_exp_f32_e32 v209, v64
	v_sub_f32_e32 v64, v66, v186
	v_exp_f32_e32 v210, v64
	v_sub_f32_e32 v64, v67, v186
	s_waitcnt lgkmcnt(0)
; #define LAS __attribute__((address_space(3)))
; __device__ __forceinline__ unsigned pk2(float lo, float hi) { f32x2_t v = {lo, hi}; bf16x2_t b = __builtin_convertvector(v, bf16x2_t); return __builtin_bit_cast(unsigned, b); }
; template <int DK, bool IS_A>
; __device__ __forceinline__ void attn_unit(const Params& P, int l, LAS unsigned char* lds, int b, int grp, int qtok0, int nkeys) {
;     ...
;             __builtin_amdgcn_s_setprio(1);
; #pragma unroll
;             for (int i = 0; i < DK / 16; ++i)
; #pragma unroll
;                 for (int jj = 0; jj < 2; ++jj) {
;                     const bf16x8 kf = *(const LAS bf16x8*)(kb + jj * 32 * AK_PITCH + i * 32);
;                     pa[jj] = __builtin_amdgcn_mfma_f32_32x32x16_bf16(kf, qa[i], pa[jj], 0, 0, 0);
;                     pb[jj] = __builtin_amdgcn_mfma_f32_32x32x16_bf16(kf, qb[i], pb[jj], 0, 0, 0);
;                 }
;             __builtin_amdgcn_s_setprio(0);
;     ...
;             for (int ks = 0; ks < 4; ++ks) {
;                 const int o8 = 8 * (ks & 1);
;                 u32x4 w; const f32x16& xa = pa[ks >> 1]; const f32x16& xb = pb[ks >> 1];
;                 w.x = pk2(xa[o8], xa[o8 + 1]); w.y = pk2(xa[o8 + 2], xa[o8 + 3]); w.z = pk2(xa[o8 + 4], xa[o8 + 5]); w.w = pk2(xa[o8 + 6], xa[o8 + 7]);
;                 const bf16x8 pfa = __builtin_bit_cast(bf16x8, w);
;                 w.x = pk2(xb[o8], xb[o8 + 1]); w.y = pk2(xb[o8 + 2], xb[o8 + 3]); w.z = pk2(xb[o8 + 4], xb[o8 + 5]); w.w = pk2(xb[o8 + 6], xb[o8 + 7]);
;                 const bf16x8 pfb = __builtin_bit_cast(bf16x8, w);
;                 const u32x2 a0 = *(const LAS u32x2*)(vb + ks * 32), a1 = *(const LAS u32x2*)(vb + ks * 32 + 16);
;                 const u32x2 c0 = *(const LAS u32x2*)(vb + 32 * AV_PITCH + ks * 32), c1 = *(const LAS u32x2*)(vb + 32 * AV_PITCH + ks * 32 + 16);
;                 const bf16x8 v0 = __builtin_bit_cast(bf16x8, ((u32x4){a0.x, a0.y, a1.x, a1.y})), v1 = __builtin_bit_cast(bf16x8, ((u32x4){c0.x, c0.y, c1.x, c1.y}));
;                 oa0 = __builtin_amdgcn_mfma_f32_32x32x16_bf16(v0, pfa, oa0, 0, 0, 0);
;                 oa1 = __builtin_amdgcn_mfma_f32_32x32x16_bf16(v1, pfa, oa1, 0, 0, 0);
;                 ob0 = __builtin_amdgcn_mfma_f32_32x32x16_bf16(v0, pfb, ob0, 0, 0, 0);
;                 ob1 = __builtin_amdgcn_mfma_f32_32x32x16_bf16(v1, pfb, ob1, 0, 0, 0);
;             }
	v_mfma_f32_32x32x16_bf16 v[32:47], v[88:91], v[84:87], v[32:47]
	v_sub_f32_e32 v84, v111, v186
	v_exp_f32_e32 v207, v84
	v_cvt_pk_bf16_f32 v84, v196, v197
	v_cvt_pk_bf16_f32 v85, v198, v199
	v_cvt_pk_bf16_f32 v86, v204, v205
	v_cvt_pk_bf16_f32 v87, v206, v207
	s_nop 1
	v_mfma_f32_32x32x16_bf16 v[16:31], v[80:83], v[84:87], v[16:31]
	v_sub_f32_e32 v80, v94, v188
	v_exp_f32_e32 v94, v80
	ds_read2_b64 v[80:83], v182 offset0:8 offset1:10
	v_mfma_f32_32x32x16_bf16 v[0:15], v[88:91], v[84:87], v[0:15]
	ds_read2_b64 v[88:91], v183 offset0:40 offset1:42
	v_cvt_pk_bf16_f32 v84, v211, v212
	v_exp_f32_e32 v211, v64
	v_sub_f32_e32 v64, v68, v186
	v_exp_f32_e32 v212, v64
	v_sub_f32_e32 v64, v69, v186
	v_cvt_pk_bf16_f32 v85, v181, v213
	v_exp_f32_e32 v213, v64
	v_sub_f32_e32 v64, v70, v186
	v_cvt_pk_bf16_f32 v86, v214, v215
	v_exp_f32_e32 v214, v64
	v_sub_f32_e32 v64, v71, v186
	v_exp_f32_e32 v215, v64
	v_cvt_pk_bf16_f32 v87, v216, v217
	v_sub_f32_e32 v68, v95, v188
	v_cvt_pk_bf16_f32 v64, v208, v209
	s_waitcnt lgkmcnt(1)
	v_mfma_f32_32x32x16_bf16 v[48:63], v[80:83], v[84:87], v[48:63]
	v_cvt_pk_bf16_f32 v65, v210, v211
	v_cvt_pk_bf16_f32 v66, v212, v213
	v_cvt_pk_bf16_f32 v67, v214, v215
	s_waitcnt lgkmcnt(0)
	v_mfma_f32_32x32x16_bf16 v[32:47], v[88:91], v[84:87], v[32:47]
	v_exp_f32_e32 v84, v68
	v_sub_f32_e32 v68, v72, v186
	v_exp_f32_e32 v216, v68
	v_sub_f32_e32 v68, v73, v186
	v_exp_f32_e32 v217, v68
	ds_read2_b64 v[68:71], v182 offset0:12 offset1:14
	v_sub_f32_e32 v72, v75, v186
	v_mfma_f32_32x32x16_bf16 v[16:31], v[80:83], v[64:67], v[16:31]
	ds_read2_b64 v[80:83], v183 offset0:44 offset1:46
	v_exp_f32_e32 v222, v72
	v_sub_f32_e32 v72, v76, v186
	v_exp_f32_e32 v223, v72
	v_sub_f32_e32 v72, v77, v186
	v_mfma_f32_32x32x16_bf16 v[0:15], v[88:91], v[64:67], v[0:15]
	v_sub_f32_e32 v64, v74, v186
	v_exp_f32_e32 v219, v64
	v_cvt_pk_bf16_f32 v64, v218, v220
	v_cvt_pk_bf16_f32 v65, v225, v226
	v_cvt_pk_bf16_f32 v66, v92, v93
	v_cvt_pk_bf16_f32 v67, v94, v84
	v_exp_f32_e32 v218, v72
	v_sub_f32_e32 v72, v78, v186
	s_waitcnt lgkmcnt(1)
	v_mfma_f32_32x32x16_bf16 v[48:63], v[68:71], v[64:67], v[48:63]
	v_exp_f32_e32 v220, v72
	s_waitcnt lgkmcnt(0)
	v_mfma_f32_32x32x16_bf16 v[32:47], v[80:83], v[64:67], v[32:47]
	v_sub_f32_e32 v64, v79, v186
	v_exp_f32_e32 v221, v64
	v_cvt_pk_bf16_f32 v64, v216, v217
	v_cvt_pk_bf16_f32 v65, v219, v222
	v_cvt_pk_bf16_f32 v66, v223, v218
	v_cvt_pk_bf16_f32 v67, v220, v221
	s_nop 1
	v_mfma_f32_32x32x16_bf16 v[16:31], v[68:71], v[64:67], v[16:31]
	v_add_f32_e32 v68, v225, v224
	v_add_f32_e32 v68, v226, v68
	v_add_f32_e32 v68, v92, v68
	v_add_f32_e32 v68, v93, v68
	v_add_f32_e32 v68, v94, v68
	v_add_f32_e32 v68, v84, v68
	v_add_f32_e32 v185, v185, v68
	v_mfma_f32_32x32x16_bf16 v[0:15], v[80:83], v[64:67], v[0:15]
	ds_read_b128 v[64:67], v187 offset:9216
	ds_read_b128 v[224:227], v187 offset:9248
	s_waitcnt lgkmcnt(1)
	v_mfma_f32_32x32x16_bf16 v[112:127], v[64:67], v[138:141], 0
	v_mfma_f32_32x32x16_bf16 v[96:111], v[64:67], v[146:149], 0
	ds_read_b128 v[64:67], v187 offset:13824
	s_waitcnt lgkmcnt(1)
	v_mfma_f32_32x32x16_bf16 v[112:127], v[224:227], v[142:145], v[112:127]
	v_mfma_f32_32x32x16_bf16 v[96:111], v[224:227], v[150:153], v[96:111]
	ds_read_b128 v[224:227], v187 offset:13856
	s_waitcnt lgkmcnt(1)
	v_mfma_f32_32x32x16_bf16 v[80:95], v[64:67], v[138:141], 0
	v_mfma_f32_32x32x16_bf16 v[64:79], v[64:67], v[146:149], 0
	s_waitcnt lgkmcnt(0)
	v_mfma_f32_32x32x16_bf16 v[80:95], v[224:227], v[142:145], v[80:95]
	v_mfma_f32_32x32x16_bf16 v[64:79], v[224:227], v[150:153], v[64:79]
	s_nop 9
	v_max_f32_e32 v181, v80, v80
	v_max_f32_e32 v187, v112, v112
	v_max_f32_e32 v181, v187, v181
	v_max3_f32 v187, v81, v114, v82
	v_max3_f32 v181, v181, v113, v115
	v_max3_f32 v187, v187, v116, v84
	v_max3_f32 v181, v181, v83, v117
	v_max3_f32 v187, v187, v118, v86
	v_max3_f32 v181, v181, v85, v119
	v_max3_f32 v187, v187, v120, v88
	v_max3_f32 v181, v181, v87, v121
	v_max3_f32 v187, v187, v122, v90
	v_max3_f32 v181, v181, v89, v123
	v_max3_f32 v187, v187, v124, v92
	v_max3_f32 v181, v181, v91, v125
	v_max3_f32 v187, v187, v126, v94
	v_max3_f32 v181, v181, v93, v127
	v_max3_f32 v181, v181, v95, v187
	ds_bpermute_b32 v187, v163, v181
	s_waitcnt lgkmcnt(0)
	v_max3_f32 v181, v188, v181, v187
	v_cmp_gt_f32_e32 vcc, v181, v188
	s_cbranch_vccz .LBB0_428
	v_sub_f32_e32 v187, v188, v181
	v_exp_f32_e32 v188, v187
	s_nop 0
	v_pk_mul_f32 v[62:63], v[62:63], v[188:189] op_sel_hi:[1,0]
	v_pk_mul_f32 v[60:61], v[60:61], v[188:189] op_sel_hi:[1,0]
	v_pk_mul_f32 v[58:59], v[58:59], v[188:189] op_sel_hi:[1,0]
	v_pk_mul_f32 v[56:57], v[56:57], v[188:189] op_sel_hi:[1,0]
	v_pk_mul_f32 v[54:55], v[54:55], v[188:189] op_sel_hi:[1,0]
	v_pk_mul_f32 v[52:53], v[52:53], v[188:189] op_sel_hi:[1,0]
	v_pk_mul_f32 v[50:51], v[50:51], v[188:189] op_sel_hi:[1,0]
	v_pk_mul_f32 v[48:49], v[48:49], v[188:189] op_sel_hi:[1,0]
	v_pk_mul_f32 v[46:47], v[46:47], v[188:189] op_sel_hi:[1,0]
	v_pk_mul_f32 v[44:45], v[44:45], v[188:189] op_sel_hi:[1,0]
	v_pk_mul_f32 v[42:43], v[42:43], v[188:189] op_sel_hi:[1,0]
	v_pk_mul_f32 v[40:41], v[40:41], v[188:189] op_sel_hi:[1,0]
	v_pk_mul_f32 v[38:39], v[38:39], v[188:189] op_sel_hi:[1,0]
	v_pk_mul_f32 v[36:37], v[36:37], v[188:189] op_sel_hi:[1,0]
	v_pk_mul_f32 v[34:35], v[34:35], v[188:189] op_sel_hi:[1,0]
	v_pk_mul_f32 v[32:33], v[32:33], v[188:189] op_sel_hi:[1,0]
	v_mul_f32_e32 v185, v185, v188
	s_branch .LBB0_429

; #define LAS __attribute__((address_space(3)))
; __device__ __forceinline__ float shx(float v, int o, int lane) { return __builtin_bit_cast(float, __builtin_amdgcn_ds_bpermute((lane ^ o) << 2, __builtin_bit_cast(int, v))); }
; template <int DK, bool IS_A>
; __device__ __forceinline__ void attn_unit(const Params& P, int l, LAS unsigned char* lds, int b, int grp, int qtok0, int nkeys) {
;     ...
;     la += shx(la, 32, lane); lb_ += shx(lb_, 32, lane);
;     { const float ia = 1.0f / la, ib = 1.0f / lb_;
; #pragma unroll
;       for (int r = 0; r < 16; ++r) { oa0[r] *= ia; oa1[r] *= ia; ob0[r] *= ib; ob1[r] *= ib; } }
;     ...
;     if (IS_A) {
;         LAS float* X = (LAS float*)lds;
;         if (s == 1) {
; #pragma unroll
;             for (int r = 0; r < 16; ++r) { X[(wq * 64 + r) * 64 + lane] = oa0[r]; X[(wq * 64 + 16 + r) * 64 + lane] = oa1[r]; X[(wq * 64 + 32 + r) * 64 + lane] = ob0[r]; X[(wq * 64 + 48 + r) * 64 + lane] = ob1[r]; }
.LBB0_434:
	s_setprio 0
	ds_bpermute_b32 v64, v163, v185
	ds_bpermute_b32 v65, v163, v180
	s_waitcnt lgkmcnt(1)
	v_add_f32_e32 v64, v185, v64
	v_div_scale_f32 v66, s[10:11], v64, v64, 1.0
	v_rcp_f32_e32 v67, v66
	s_waitcnt lgkmcnt(0)
	v_add_f32_e32 v65, v180, v65
	v_fma_f32 v68, -v66, v67, 1.0
	v_fmac_f32_e32 v67, v68, v67
	v_div_scale_f32 v68, vcc, 1.0, v64, 1.0
	v_mul_f32_e32 v69, v68, v67
	v_fma_f32 v70, -v66, v69, v68
	v_fmac_f32_e32 v69, v70, v67
	v_fma_f32 v66, -v66, v69, v68
	v_div_fmas_f32 v66, v66, v67, v69
	v_div_fixup_f32 v72, v66, v64, 1.0
	v_div_scale_f32 v64, s[10:11], v65, v65, 1.0
	v_rcp_f32_e32 v66, v64
	v_pk_mul_f32 v[36:37], v[36:37], v[72:73] op_sel_hi:[1,0]
	v_pk_mul_f32 v[70:71], v[54:55], v[72:73] op_sel_hi:[1,0]
	v_pk_mul_f32 v[56:57], v[56:57], v[72:73] op_sel_hi:[1,0]
	v_fma_f32 v67, -v64, v66, 1.0
	v_fmac_f32_e32 v66, v67, v66
	v_div_scale_f32 v67, vcc, 1.0, v65, 1.0
	v_mul_f32_e32 v68, v67, v66
	v_fma_f32 v69, -v64, v68, v67
	v_fmac_f32_e32 v68, v69, v66
	v_fma_f32 v64, -v64, v68, v67
	v_div_fmas_f32 v64, v64, v66, v68
	v_div_fixup_f32 v74, v64, v65, 1.0
	v_pk_mul_f32 v[66:67], v[50:51], v[72:73] op_sel_hi:[1,0]
	v_pk_mul_f32 v[50:51], v[34:35], v[72:73] op_sel_hi:[1,0]
	v_pk_mul_f32 v[34:35], v[18:19], v[74:75] op_sel_hi:[1,0]
	v_pk_mul_f32 v[18:19], v[2:3], v[74:75] op_sel_hi:[1,0]
	v_pk_mul_f32 v[2:3], v[6:7], v[74:75] op_sel_hi:[1,0]
	v_pk_mul_f32 v[6:7], v[24:25], v[74:75] op_sel_hi:[1,0]
	v_pk_mul_f32 v[24:25], v[28:29], v[74:75] op_sel_hi:[1,0]
	v_pk_mul_f32 v[28:29], v[14:15], v[74:75] op_sel_hi:[1,0]
	v_lshlrev_b32_e32 v14, 8, v173
	v_pk_mul_f32 v[64:65], v[48:49], v[72:73] op_sel_hi:[1,0]
	v_pk_mul_f32 v[48:49], v[32:33], v[72:73] op_sel_hi:[1,0]
	v_pk_mul_f32 v[32:33], v[16:17], v[74:75] op_sel_hi:[1,0]
	v_pk_mul_f32 v[16:17], v[0:1], v[74:75] op_sel_hi:[1,0]
	v_pk_mul_f32 v[68:69], v[52:53], v[72:73] op_sel_hi:[1,0]
	v_pk_mul_f32 v[20:21], v[20:21], v[74:75] op_sel_hi:[1,0]
	v_pk_mul_f32 v[0:1], v[4:5], v[74:75] op_sel_hi:[1,0]
	v_pk_mul_f32 v[52:53], v[38:39], v[72:73] op_sel_hi:[1,0]
	v_pk_mul_f32 v[22:23], v[22:23], v[74:75] op_sel_hi:[1,0]
	v_pk_mul_f32 v[54:55], v[40:41], v[72:73] op_sel_hi:[1,0]
	v_pk_mul_f32 v[4:5], v[8:9], v[74:75] op_sel_hi:[1,0]
	v_pk_mul_f32 v[38:39], v[58:59], v[72:73] op_sel_hi:[1,0]
	v_pk_mul_f32 v[40:41], v[42:43], v[72:73] op_sel_hi:[1,0]
	v_pk_mul_f32 v[8:9], v[26:27], v[74:75] op_sel_hi:[1,0]
	v_pk_mul_f32 v[10:11], v[10:11], v[74:75] op_sel_hi:[1,0]
	v_pk_mul_f32 v[42:43], v[60:61], v[72:73] op_sel_hi:[1,0]
	v_pk_mul_f32 v[44:45], v[44:45], v[72:73] op_sel_hi:[1,0]
	v_pk_mul_f32 v[12:13], v[12:13], v[74:75] op_sel_hi:[1,0]
	v_pk_mul_f32 v[58:59], v[62:63], v[72:73] op_sel_hi:[1,0]
	v_pk_mul_f32 v[46:47], v[46:47], v[72:73] op_sel_hi:[1,0]
	v_pk_mul_f32 v[26:27], v[30:31], v[74:75] op_sel_hi:[1,0]
	v_cmp_eq_u32_e32 vcc, 1, v172
	v_add3_u32 v60, 0, v174, v14
	s_and_saveexec_b64 s[10:11], vcc
	s_cbranch_execz .LBB0_436
	ds_write2st64_b32 v60, v64, v65 offset1:1
	ds_write2st64_b32 v60, v48, v49 offset0:16 offset1:17
	ds_write2st64_b32 v60, v32, v33 offset0:32 offset1:33
	ds_write2st64_b32 v60, v16, v17 offset0:48 offset1:49
	ds_write2st64_b32 v60, v66, v67 offset0:2 offset1:3
	ds_write2st64_b32 v60, v50, v51 offset0:18 offset1:19
	ds_write2st64_b32 v60, v34, v35 offset0:34 offset1:35
	ds_write2st64_b32 v60, v18, v19 offset0:50 offset1:51
	ds_write2st64_b32 v60, v68, v69 offset0:4 offset1:5
	ds_write2st64_b32 v60, v36, v37 offset0:20 offset1:21
	ds_write2st64_b32 v60, v20, v21 offset0:36 offset1:37
	ds_write2st64_b32 v60, v0, v1 offset0:52 offset1:53
	ds_write2st64_b32 v60, v70, v71 offset0:6 offset1:7
	ds_write2st64_b32 v60, v52, v53 offset0:22 offset1:23
	ds_write2st64_b32 v60, v22, v23 offset0:38 offset1:39
	ds_write2st64_b32 v60, v2, v3 offset0:54 offset1:55
	ds_write2st64_b32 v60, v56, v57 offset0:8 offset1:9
	ds_write2st64_b32 v60, v54, v55 offset0:24 offset1:25
	ds_write2st64_b32 v60, v6, v7 offset0:40 offset1:41
	ds_write2st64_b32 v60, v4, v5 offset0:56 offset1:57
	ds_write2st64_b32 v60, v38, v39 offset0:10 offset1:11
	ds_write2st64_b32 v60, v40, v41 offset0:26 offset1:27
	ds_write2st64_b32 v60, v8, v9 offset0:42 offset1:43
	ds_write2st64_b32 v60, v10, v11 offset0:58 offset1:59
	ds_write2st64_b32 v60, v42, v43 offset0:12 offset1:13
	ds_write2st64_b32 v60, v44, v45 offset0:28 offset1:29
	ds_write2st64_b32 v60, v24, v25 offset0:44 offset1:45
	ds_write2st64_b32 v60, v12, v13 offset0:60 offset1:61
	ds_write2st64_b32 v60, v58, v59 offset0:14 offset1:15
	ds_write2st64_b32 v60, v46, v47 offset0:30 offset1:31
	ds_write2st64_b32 v60, v26, v27 offset0:46 offset1:47
	ds_write2st64_b32 v60, v28, v29 offset0:62 offset1:63

; __device__ __forceinline__ int opaque_tid() { int t = threadIdx.x; asm volatile("" : "+v"(t)); return t; }
; #define AT_LOAD(t_) do { const bf16_t* kn = ksrc + (size_t)(t_) * AKT * INW; const bf16_t* vn = vsrc + (t_) * AKT; \
;         kreg0 = *(const u32x4*)kn; kreg1 = *(const u32x4*)(kn + (size_t)64 * INW); vreg0 = *(const u32x4*)vn; vreg1 = *(const u32x4*)(vn + 64); } while (0)
; template <int DK, bool IS_A>
; __device__ __forceinline__ void attn_unit(const Params& P, int l, LAS unsigned char* lds, int b, int grp, int qtok0, int nkeys) {
;     const int tid = opaque_tid(), lane = tid & 63, wave = tid >> 6, s = wave >> 2, wq = wave & 3, r32 = lane & 31, hi = lane >> 5;
;     const bf16_t* proj = (const bf16_t*)(P.ws + WS_PROJ);
;     bf16_t* mix = (bf16_t*)(P.ws + WS_H);
;     const int qcol = IS_A ? PA_Q + grp * 64 + s * 32 : PC_Q + (2 * grp + s) * 64;
;     const int kcol = IS_A ? PA_K + grp * 64 : PC_K + grp * 64;
;     const int koff = IS_A ? s * 32 : 0;
;     const bf16_t* VT = IS_A ? (const bf16_t*)(P.ws + WS_VTA) + ((size_t)(b * 4 + grp) * 64) * TT : (const bf16_t*)(P.ws + WS_VTC) + ((size_t)(b * 2 + grp) * 64) * TT;
;     const size_t qrow = (size_t)b * TT + qtok0 + wq * 64 + r32;
;     bf16x8 qa[DK / 16], qb[DK / 16];
; #pragma unroll
;     for (int i = 0; i < DK / 16; ++i) { qa[i] = *(const bf16x8*)(proj + qrow * INW + qcol + i * 16 + hi * 8); qb[i] = *(const bf16x8*)(proj + (qrow + 32) * INW + qcol + i * 16 + hi * 8); }
;     const int lrow = tid >> 3, lch = tid & 7;
;     const bf16_t* ksrc = proj + ((size_t)b * TT + lrow) * INW + kcol + lch * 8;
;     const bf16_t* vsrc = VT + (size_t)lrow * TT + lch * 8;
;     const int NT = nkeys / AKT;
;     u32x4 kreg0, kreg1, vreg0, vreg1;
;     ...
;     const int kfo = r32 * AK_PITCH + (koff + 8 * hi) * 2, vfo = AK_BYTES + r32 * AV_PITCH + 8 * hi;
;     AT_LOAD(0); AT_STORE(0);
;     __syncthreads();
;     float ma = -1e30f, mb = -1e30f, la = 0.f, lb_ = 0.f;
;     f32x16 oa0, oa1, ob0, ob1;
; #pragma unroll
;     for (int r = 0; r < 16; ++r) { oa0[r] = 0.f; oa1[r] = 0.f; ob0[r] = 0.f; ob1[r] = 0.f; }
.LBB0_440:
	s_andn2_b64 vcc, exec, s[10:11]
	s_cbranch_vccnz .LBB0_460
	s_add_i32 s8, s37, 0xffffff60
	s_lshr_b32 s15, s8, 4
	s_lshl_b32 s8, s37, 8
	s_bfe_u32 s18, s37, 0x10003
	s_and_b32 s9, s8, 0x700
	s_mul_i32 s8, s15, 0x900
	v_mov_b32_e32 v12, v200
	s_add_i32 s9, s9, s8
	s_lshl_b32 s11, s18, 6
	s_lshl_b32 s12, s15, 7
	v_ashrrev_i32_e32 v2, 3, v12
	s_or_b32 s11, s11, s12
	s_add_i32 s19, s9, 0x100
	s_mov_b32 s9, s65
	v_ashrrev_i32_e32 v3, 31, v2
	s_mul_i32 s64, s11, 0x900
	v_mov_b64_e32 v[0:1], s[56:57]
	v_lshl_add_u64 v[4:5], v[2:3], 0, s[8:9]
	s_lshl_b32 s10, s18, 7
	s_lshl_b64 s[12:13], s[64:65], 1
	v_mad_u64_u32 v[6:7], s[8:9], v4, s23, v[0:1]
	s_add_u32 s12, s20, s12
	v_readlane_b32 s7, v255, 5
	v_mad_i32_i24 v7, v5, s23, v7
	s_mov_b32 s11, s65
	v_lshlrev_b32_e32 v3, 4, v12
	s_addc_u32 s13, s7, s13
	v_lshl_add_u64 v[6:7], v[6:7], 0, s[10:11]
	v_and_b32_e32 v190, 0x70, v3
	v_mov_b32_e32 v191, v129
	v_lshl_add_u64 v[6:7], v[6:7], 0, v[190:191]
	v_mov_b64_e32 v[8:9], s[12:13]
	s_movk_i32 s7, 0x1000
	v_mad_i64_i32 v[8:9], s[8:9], v2, s27, v[8:9]
	v_add_co_u32_e32 v10, vcc, s7, v6
	s_mov_b32 s8, 0x59000
	s_nop 0
	v_addc_co_u32_e32 v11, vcc, 0, v7, vcc
	v_add_co_u32_e32 v6, vcc, s8, v6
	v_lshl_add_u64 v[8:9], v[8:9], 0, v[190:191]
	s_nop 0
	v_addc_co_u32_e32 v7, vcc, 0, v7, vcc
	global_load_dwordx4 v[130:133], v[10:11], off offset:512
	global_load_dwordx4 v[134:137], v[6:7], off offset:512
	global_load_dwordx4 v[138:141], v[8:9], off
	global_load_dwordx4 v[150:153], v[8:9], off offset:128
	v_ashrrev_i32_e32 v6, 2, v12
	v_and_b32_e32 v3, 0xc0, v12
	v_and_b32_e32 v13, 31, v12
	v_and_b32_e32 v6, 0xffffffc0, v6
	v_add_u32_e32 v188, s10, v6
	v_or3_b32 v128, s19, v3, v13
	v_bfe_u32 v14, v12, 5, 1
	v_mad_u64_u32 v[0:1], s[8:9], v128, s23, v[0:1]
	v_ashrrev_i32_e32 v189, 31, v188
	v_lshl_add_u64 v[0:1], v[188:189], 1, v[0:1]
	v_lshlrev_b32_e32 v192, 4, v14
	v_mov_b32_e32 v193, v129
	v_lshl_add_u64 v[0:1], v[0:1], 0, v[192:193]
	s_mov_b64 s[8:9], 0x1000
	v_add_co_u32_e32 v10, vcc, s7, v0
	v_lshl_add_u64 v[6:7], v[0:1], 0, s[8:9]
	s_mov_b64 s[8:9], 0x2d000
	v_addc_co_u32_e32 v11, vcc, 0, v1, vcc
	s_mov_b32 s7, 0x2d000
	v_lshl_add_u64 v[8:9], v[0:1], 0, s[8:9]
	v_add_co_u32_e32 v0, vcc, s7, v0
	s_movk_i32 s7, 0x90
	s_nop 0
	v_addc_co_u32_e32 v1, vcc, 0, v1, vcc
	global_load_dwordx4 v[142:145], v[10:11], off
	global_load_dwordx4 v[146:149], v[0:1], off
	global_load_dwordx4 v[154:157], v[6:7], off offset:32
	global_load_dwordx4 v[158:161], v[6:7], off offset:64
	global_load_dwordx4 v[162:165], v[8:9], off offset:32
	global_load_dwordx4 v[166:169], v[6:7], off offset:96
	global_load_dwordx4 v[170:173], v[8:9], off offset:64
	global_load_dwordx4 v[174:177], v[8:9], off offset:96
	v_mul_lo_u32 v179, v2, s7
	s_movk_i32 s7, 0x108
	v_and_b32_e32 v1, 63, v12
	v_mul_lo_u32 v180, v2, s7
	v_add3_u32 v0, 0, v179, v190
	s_movk_i32 s7, 0x78
	s_mul_i32 s9, s15, 0x48000
	s_mul_i32 s18, s18, 0x24000
	v_mad_u64_u32 v[6:7], s[12:13], v2, s7, v[0:1]
	s_add_i32 s64, s9, s18
	s_lshl_b64 s[12:13], s[64:65], 1
	s_add_u32 s12, s54, s12
	v_add_u32_e32 v3, 0x4800, v6
	s_addc_u32 s13, s55, s13
	s_waitcnt vmcnt(11)
	ds_write_b128 v0, v[130:133]
	s_waitcnt vmcnt(10)
	ds_write_b128 v0, v[134:137] offset:9216
	s_waitcnt vmcnt(9)
	ds_write2_b64 v3, v[138:139], v[140:141] offset1:1
	v_add_u32_e32 v0, 0x4880, v6
	s_waitcnt vmcnt(8)
	ds_write2_b64 v0, v[150:151], v[152:153] offset1:1
	v_lshlrev_b32_e32 v0, 2, v1
	s_add_u32 s10, s54, s10
	v_xor_b32_e32 v181, 0x80, v0
	v_mov_b64_e32 v[0:1], s[12:13]
	s_addc_u32 s11, s55, 0
	v_mad_i64_i32 v[194:195], s[12:13], v2, s27, v[0:1]
	v_mov_b64_e32 v[0:1], s[10:11]
	v_lshlrev_b32_e32 v186, 3, v14
	v_mad_u64_u32 v[196:197], s[10:11], v4, s23, v[0:1]
	v_mov_b32_e32 v14, v129
	v_mov_b32_e32 v15, v129
	v_mul_u32_u24_e32 v178, 0x90, v13
	v_mul_u32_u24_e32 v182, 0x108, v13
	v_mad_i32_i24 v197, v5, s23, v197
	v_mov_b32_e32 v0, v129
	v_mov_b32_e32 v1, v129
	v_mov_b32_e32 v2, v129
	v_mov_b32_e32 v3, v129
	v_mov_b32_e32 v4, v129
	v_mov_b32_e32 v5, v129
	v_mov_b32_e32 v6, v129
	v_mov_b32_e32 v7, v129
	v_mov_b32_e32 v8, v129
	v_mov_b32_e32 v9, v129
	v_mov_b32_e32 v10, v129
	v_mov_b32_e32 v11, v129
	v_mov_b32_e32 v12, v129
	v_mov_b32_e32 v13, v129
	v_mov_b64_e32 v[30:31], v[14:15]
	v_mov_b64_e32 v[46:47], v[14:15]
	v_mov_b64_e32 v[62:63], v[14:15]
	s_mov_b32 s8, 0
	v_mov_b32_e32 v198, 0
	v_mov_b32_e32 v184, 0xf149f2ca
	v_mov_b32_e32 v193, 0xf149f2ca
	v_mov_b32_e32 v183, 0
	v_mov_b64_e32 v[28:29], v[12:13]
	v_mov_b64_e32 v[26:27], v[10:11]
	v_mov_b64_e32 v[24:25], v[8:9]
	v_mov_b64_e32 v[22:23], v[6:7]
	v_mov_b64_e32 v[20:21], v[4:5]
	v_mov_b64_e32 v[18:19], v[2:3]
	v_mov_b64_e32 v[16:17], v[0:1]
	v_mov_b64_e32 v[44:45], v[12:13]
	v_mov_b64_e32 v[42:43], v[10:11]
	v_mov_b64_e32 v[40:41], v[8:9]
	v_mov_b64_e32 v[38:39], v[6:7]
	v_mov_b64_e32 v[36:37], v[4:5]
	v_mov_b64_e32 v[34:35], v[2:3]
	v_mov_b64_e32 v[32:33], v[0:1]
	v_mov_b64_e32 v[60:61], v[12:13]
	v_mov_b64_e32 v[58:59], v[10:11]
	v_mov_b64_e32 v[56:57], v[8:9]
	v_mov_b64_e32 v[54:55], v[6:7]
	v_mov_b64_e32 v[52:53], v[4:5]
	v_mov_b64_e32 v[50:51], v[2:3]
	v_mov_b64_e32 v[48:49], v[0:1]
	s_waitcnt lgkmcnt(0)
	s_waitcnt vmcnt(0)
	s_mov_b32 s100, 0
	v_readfirstlane_b32 s101, v200
	s_nop 3
	s_lshr_b32 s101, s101, 8
	s_cmp_eq_u32 s101, 0
	s_cbranch_scc1 .Lsp_c
	s_setprio 1

; #define LAS __attribute__((address_space(3)))
; template <int DK, bool IS_A>
; __device__ __forceinline__ void attn_unit(const Params& P, int l, LAS unsigned char* lds, int b, int grp, int qtok0, int nkeys) {
;     ...
;         for (int h = 0; h < 2; ++h) {
;             const LAS unsigned char* kb = lds + buf * A_BUF + kfo + h * 64 * AK_PITCH;
;             const LAS unsigned char* vb = lds + buf * A_BUF + vfo + h * 128;
;             f32x16 pa[2], pb[2];
; #pragma unroll
;             for (int jj = 0; jj < 2; ++jj)
; #pragma unroll
;                 for (int r = 0; r < 16; ++r) { pa[jj][r] = 0.f; pb[jj][r] = 0.f; }
;             __builtin_amdgcn_s_setprio(1);
; #pragma unroll
;             for (int i = 0; i < DK / 16; ++i)
; #pragma unroll
;                 for (int jj = 0; jj < 2; ++jj) {
;                     const bf16x8 kf = *(const LAS bf16x8*)(kb + jj * 32 * AK_PITCH + i * 32);
;                     pa[jj] = __builtin_amdgcn_mfma_f32_32x32x16_bf16(kf, qa[i], pa[jj], 0, 0, 0);
;                     pb[jj] = __builtin_amdgcn_mfma_f32_32x32x16_bf16(kf, qb[i], pb[jj], 0, 0, 0);
;                 }
;             __builtin_amdgcn_s_setprio(0);
.LBB0_445:
	s_mov_b32 s12, s100
	v_add_u32_e32 v64, s12, v178
	v_add_u32_e32 v199, v64, v192
	ds_read_b128 v[64:67], v199
	ds_read_b128 v[204:207], v199 offset:32
	s_waitcnt lgkmcnt(1)
	v_mfma_f32_32x32x16_bf16 v[112:127], v[64:67], v[142:145], 0
	v_mfma_f32_32x32x16_bf16 v[96:111], v[64:67], v[146:149], 0
	ds_read_b128 v[64:67], v199 offset:4608
	s_waitcnt lgkmcnt(1)
	v_mfma_f32_32x32x16_bf16 v[112:127], v[204:207], v[154:157], v[112:127]
	v_mfma_f32_32x32x16_bf16 v[96:111], v[204:207], v[162:165], v[96:111]
	ds_read_b128 v[204:207], v199 offset:4640
	s_waitcnt lgkmcnt(1)
	v_mfma_f32_32x32x16_bf16 v[80:95], v[64:67], v[142:145], 0
	v_mfma_f32_32x32x16_bf16 v[64:79], v[64:67], v[146:149], 0
	s_waitcnt lgkmcnt(0)
	v_mfma_f32_32x32x16_bf16 v[80:95], v[204:207], v[154:157], v[80:95]
	v_mfma_f32_32x32x16_bf16 v[64:79], v[204:207], v[162:165], v[64:79]
	ds_read_b128 v[204:207], v199 offset:64
	s_waitcnt lgkmcnt(0)
	v_mfma_f32_32x32x16_bf16 v[112:127], v[204:207], v[158:161], v[112:127]
	v_mfma_f32_32x32x16_bf16 v[96:111], v[204:207], v[170:173], v[96:111]
	ds_read_b128 v[204:207], v199 offset:4672
	s_waitcnt lgkmcnt(0)
	v_mfma_f32_32x32x16_bf16 v[80:95], v[204:207], v[158:161], v[80:95]
	v_mfma_f32_32x32x16_bf16 v[64:79], v[204:207], v[170:173], v[64:79]
	ds_read_b128 v[204:207], v199 offset:96
	s_waitcnt lgkmcnt(0)
	v_mfma_f32_32x32x16_bf16 v[112:127], v[204:207], v[166:169], v[112:127]
	v_mfma_f32_32x32x16_bf16 v[96:111], v[204:207], v[174:177], v[96:111]
	ds_read_b128 v[204:207], v199 offset:4704
	s_waitcnt lgkmcnt(0)
	v_mfma_f32_32x32x16_bf16 v[80:95], v[204:207], v[166:169], v[80:95]
	v_mfma_f32_32x32x16_bf16 v[64:79], v[204:207], v[174:177], v[64:79]
	s_nop 9
	v_max_f32_e32 v185, v80, v80
	v_max_f32_e32 v187, v112, v112
	v_max_f32_e32 v185, v187, v185
	v_max3_f32 v187, v81, v114, v82
	v_max3_f32 v185, v185, v113, v115
	v_max3_f32 v187, v187, v116, v84
	v_max3_f32 v185, v185, v83, v117
	v_max3_f32 v187, v187, v118, v86
	v_max3_f32 v185, v185, v85, v119
	v_max3_f32 v187, v187, v120, v88
	v_max3_f32 v185, v185, v87, v121
	v_max3_f32 v187, v187, v122, v90
	v_max3_f32 v185, v185, v89, v123
	v_max3_f32 v187, v187, v124, v92
	v_max3_f32 v185, v185, v91, v125
	v_max3_f32 v187, v187, v126, v94
	v_max3_f32 v185, v185, v93, v127
	v_max3_f32 v185, v185, v95, v187
	ds_bpermute_b32 v187, v181, v185
	s_waitcnt lgkmcnt(0)
	v_max3_f32 v205, v184, v185, v187
	v_cmp_gt_f32_e32 vcc, v205, v184
	s_cbranch_vccz .LBB0_447
	v_sub_f32_e32 v184, v184, v205
	v_exp_f32_e32 v184, v184
	s_nop 0
	v_pk_mul_f32 v[62:63], v[62:63], v[184:185] op_sel_hi:[1,0]
	v_pk_mul_f32 v[60:61], v[60:61], v[184:185] op_sel_hi:[1,0]
	v_pk_mul_f32 v[58:59], v[58:59], v[184:185] op_sel_hi:[1,0]
	v_pk_mul_f32 v[56:57], v[56:57], v[184:185] op_sel_hi:[1,0]
	v_pk_mul_f32 v[54:55], v[54:55], v[184:185] op_sel_hi:[1,0]
	v_pk_mul_f32 v[52:53], v[52:53], v[184:185] op_sel_hi:[1,0]
	v_pk_mul_f32 v[50:51], v[50:51], v[184:185] op_sel_hi:[1,0]
	v_pk_mul_f32 v[48:49], v[48:49], v[184:185] op_sel_hi:[1,0]
	v_pk_mul_f32 v[46:47], v[46:47], v[184:185] op_sel_hi:[1,0]
	v_pk_mul_f32 v[44:45], v[44:45], v[184:185] op_sel_hi:[1,0]
	v_pk_mul_f32 v[42:43], v[42:43], v[184:185] op_sel_hi:[1,0]
	v_pk_mul_f32 v[40:41], v[40:41], v[184:185] op_sel_hi:[1,0]
	v_pk_mul_f32 v[38:39], v[38:39], v[184:185] op_sel_hi:[1,0]
	v_pk_mul_f32 v[36:37], v[36:37], v[184:185] op_sel_hi:[1,0]
	v_pk_mul_f32 v[34:35], v[34:35], v[184:185] op_sel_hi:[1,0]
	v_pk_mul_f32 v[32:33], v[32:33], v[184:185] op_sel_hi:[1,0]
	v_mul_f32_e32 v198, v198, v184
	s_branch .LBB0_448

; #define LAS __attribute__((address_space(3)))
; __device__ __forceinline__ unsigned pk2(float lo, float hi) { f32x2_t v = {lo, hi}; bf16x2_t b = __builtin_convertvector(v, bf16x2_t); return __builtin_bit_cast(unsigned, b); }
; template <int DK, bool IS_A>
; __device__ __forceinline__ void attn_unit(const Params& P, int l, LAS unsigned char* lds, int b, int grp, int qtok0, int nkeys) {
;     ...
;             AT_SOFTMAX(pa, ma, la, oa0, oa1);
;             AT_SOFTMAX(pb, mb, lb_, ob0, ob1);
;     ...
; #pragma unroll
;             for (int ks = 0; ks < 4; ++ks) {
;                 const int o8 = 8 * (ks & 1);
;                 u32x4 w; const f32x16& xa = pa[ks >> 1]; const f32x16& xb = pb[ks >> 1];
;                 w.x = pk2(xa[o8], xa[o8 + 1]); w.y = pk2(xa[o8 + 2], xa[o8 + 3]); w.z = pk2(xa[o8 + 4], xa[o8 + 5]); w.w = pk2(xa[o8 + 6], xa[o8 + 7]);
;                 const bf16x8 pfa = __builtin_bit_cast(bf16x8, w);
;                 w.x = pk2(xb[o8], xb[o8 + 1]); w.y = pk2(xb[o8 + 2], xb[o8 + 3]); w.z = pk2(xb[o8 + 4], xb[o8 + 5]); w.w = pk2(xb[o8 + 6], xb[o8 + 7]);
;                 const bf16x8 pfb = __builtin_bit_cast(bf16x8, w);
;                 const u32x2 a0 = *(const LAS u32x2*)(vb + ks * 32), a1 = *(const LAS u32x2*)(vb + ks * 32 + 16);
;                 const u32x2 c0 = *(const LAS u32x2*)(vb + 32 * AV_PITCH + ks * 32), c1 = *(const LAS u32x2*)(vb + 32 * AV_PITCH + ks * 32 + 16);
;                 const bf16x8 v0 = __builtin_bit_cast(bf16x8, ((u32x4){a0.x, a0.y, a1.x, a1.y})), v1 = __builtin_bit_cast(bf16x8, ((u32x4){c0.x, c0.y, c1.x, c1.y}));
;                 oa0 = __builtin_amdgcn_mfma_f32_32x32x16_bf16(v0, pfa, oa0, 0, 0, 0);
;                 oa1 = __builtin_amdgcn_mfma_f32_32x32x16_bf16(v1, pfa, oa1, 0, 0, 0);
;                 ob0 = __builtin_amdgcn_mfma_f32_32x32x16_bf16(v0, pfb, ob0, 0, 0, 0);
;                 ob1 = __builtin_amdgcn_mfma_f32_32x32x16_bf16(v1, pfb, ob1, 0, 0, 0);
;             }
.LBB0_451:
	v_sub_f32_e32 v112, v112, v205
	v_exp_f32_e32 v112, v112
	v_sub_f32_e32 v113, v113, v205
	v_exp_f32_e32 v113, v113
	v_sub_f32_e32 v114, v114, v205
	v_exp_f32_e32 v114, v114
	v_sub_f32_e32 v115, v115, v205
	v_exp_f32_e32 v115, v115
	v_sub_f32_e32 v116, v116, v205
	v_add_f32_e32 v184, 0, v112
	v_exp_f32_e32 v116, v116
	v_sub_f32_e32 v117, v117, v205
	v_add_f32_e32 v184, v113, v184
	v_exp_f32_e32 v117, v117
	v_sub_f32_e32 v118, v118, v205
	v_add_f32_e32 v184, v114, v184
	v_exp_f32_e32 v118, v118
	v_sub_f32_e32 v119, v119, v205
	v_add_f32_e32 v184, v115, v184
	v_exp_f32_e32 v119, v119
	v_sub_f32_e32 v120, v120, v205
	v_add_f32_e32 v184, v116, v184
	v_exp_f32_e32 v120, v120
	v_sub_f32_e32 v121, v121, v205
	v_add_f32_e32 v184, v117, v184
	v_exp_f32_e32 v121, v121
	v_sub_f32_e32 v122, v122, v205
	v_add_f32_e32 v184, v118, v184
	v_exp_f32_e32 v122, v122
	v_sub_f32_e32 v123, v123, v205
	v_add_f32_e32 v184, v119, v184
	v_exp_f32_e32 v123, v123
	v_sub_f32_e32 v124, v124, v205
	v_add_f32_e32 v184, v120, v184
	v_exp_f32_e32 v124, v124
	v_sub_f32_e32 v125, v125, v205
	v_add_f32_e32 v184, v121, v184
	v_exp_f32_e32 v125, v125
	v_sub_f32_e32 v126, v126, v205
	v_add_f32_e32 v184, v122, v184
	v_exp_f32_e32 v126, v126
	v_sub_f32_e32 v127, v127, v205
	v_add_f32_e32 v184, v123, v184
	v_exp_f32_e32 v127, v127
	v_sub_f32_e32 v80, v80, v205
	v_add_f32_e32 v184, v124, v184
	v_exp_f32_e32 v224, v80
	v_sub_f32_e32 v80, v81, v205
	v_add_f32_e32 v184, v125, v184
	v_exp_f32_e32 v225, v80
	v_sub_f32_e32 v81, v82, v205
	v_add_f32_e32 v80, v126, v184
	v_exp_f32_e32 v184, v81
	v_sub_f32_e32 v81, v83, v205
	v_add_f32_e32 v80, v127, v80
	v_exp_f32_e32 v226, v81
	v_sub_f32_e32 v81, v84, v205
	v_add_f32_e32 v80, v224, v80
	v_exp_f32_e32 v227, v81
	v_sub_f32_e32 v81, v85, v205
	v_add_f32_e32 v80, v225, v80
	v_exp_f32_e32 v228, v81
	v_sub_f32_e32 v81, v86, v205
	v_add_f32_e32 v80, v184, v80
	v_exp_f32_e32 v229, v81
	v_sub_f32_e32 v81, v87, v205
	v_add_f32_e32 v80, v226, v80
	v_exp_f32_e32 v230, v81
	v_sub_f32_e32 v81, v88, v205
	v_add_f32_e32 v80, v227, v80
	v_exp_f32_e32 v231, v81
	v_sub_f32_e32 v81, v89, v205
	v_add_f32_e32 v80, v228, v80
	v_exp_f32_e32 v233, v81
	v_add_f32_e32 v80, v229, v80
	v_add_f32_e32 v80, v230, v80
	v_add_f32_e32 v80, v231, v80
	v_add_f32_e32 v237, v233, v80
	v_sub_f32_e32 v80, v90, v205
	v_exp_f32_e32 v238, v80
	v_sub_f32_e32 v80, v91, v205
	v_exp_f32_e32 v239, v80
	v_sub_f32_e32 v80, v92, v205
	v_exp_f32_e32 v92, v80
	v_add_u32_e32 v80, s12, v182
	v_sub_f32_e32 v81, v96, v204
	v_add_u32_e32 v88, v80, v186
	v_exp_f32_e32 v193, v81
	v_sub_f32_e32 v81, v97, v204
	v_add_u32_e32 v185, 0x4800, v88
	v_add_u32_e32 v187, 0x6800, v88
	v_exp_f32_e32 v206, v81
	ds_read2_b64 v[80:83], v185 offset1:2
	ds_read2_b64 v[88:91], v187 offset0:32 offset1:34
	v_sub_f32_e32 v96, v99, v204
	v_sub_f32_e32 v84, v98, v204
	v_exp_f32_e32 v208, v96
	v_sub_f32_e32 v96, v100, v204
	v_exp_f32_e32 v207, v84
	v_cvt_pk_bf16_f32 v84, v112, v113
	v_cvt_pk_bf16_f32 v85, v114, v115
	v_cvt_pk_bf16_f32 v86, v116, v117
	v_cvt_pk_bf16_f32 v87, v118, v119
	v_exp_f32_e32 v209, v96
	v_sub_f32_e32 v96, v101, v204
	s_waitcnt lgkmcnt(1)
	v_mfma_f32_32x32x16_bf16 v[48:63], v[80:83], v[84:87], v[48:63]
	v_exp_f32_e32 v210, v96
	v_sub_f32_e32 v96, v102, v204
	v_exp_f32_e32 v211, v96
	v_sub_f32_e32 v96, v107, v204
	v_exp_f32_e32 v216, v96
	v_sub_f32_e32 v96, v108, v204
	v_exp_f32_e32 v217, v96
	s_waitcnt lgkmcnt(0)
	v_mfma_f32_32x32x16_bf16 v[32:47], v[88:91], v[84:87], v[32:47]
	v_sub_f32_e32 v84, v103, v204
	v_exp_f32_e32 v212, v84
	v_cvt_pk_bf16_f32 v84, v193, v206
	v_cvt_pk_bf16_f32 v85, v207, v208
	v_cvt_pk_bf16_f32 v86, v209, v210
	v_cvt_pk_bf16_f32 v87, v211, v212
	v_sub_f32_e32 v96, v109, v204
	v_exp_f32_e32 v218, v96
	v_mfma_f32_32x32x16_bf16 v[16:31], v[80:83], v[84:87], v[16:31]
	v_sub_f32_e32 v80, v93, v205
	v_exp_f32_e32 v93, v80
	v_sub_f32_e32 v80, v104, v204
	v_exp_f32_e32 v213, v80
	v_sub_f32_e32 v80, v105, v204
	v_exp_f32_e32 v214, v80
	ds_read2_b64 v[80:83], v185 offset0:4 offset1:6
	v_mfma_f32_32x32x16_bf16 v[0:15], v[88:91], v[84:87], v[0:15]
	ds_read2_b64 v[88:91], v187 offset0:36 offset1:38
	v_sub_f32_e32 v84, v106, v204
	v_exp_f32_e32 v215, v84
	v_cvt_pk_bf16_f32 v84, v120, v121
	v_cvt_pk_bf16_f32 v85, v122, v123
	v_cvt_pk_bf16_f32 v86, v124, v125
	v_cvt_pk_bf16_f32 v87, v126, v127
	v_sub_f32_e32 v96, v110, v204
	v_exp_f32_e32 v219, v96
	s_waitcnt lgkmcnt(1)
	v_mfma_f32_32x32x16_bf16 v[48:63], v[80:83], v[84:87], v[48:63]
	v_sub_f32_e32 v64, v64, v204
	v_exp_f32_e32 v221, v64
	v_sub_f32_e32 v64, v65, v204
	v_exp_f32_e32 v222, v64
	v_sub_f32_e32 v64, v66, v204
	v_exp_f32_e32 v223, v64
	v_sub_f32_e32 v64, v67, v204
	s_waitcnt lgkmcnt(0)
	v_mfma_f32_32x32x16_bf16 v[32:47], v[88:91], v[84:87], v[32:47]
	v_sub_f32_e32 v84, v111, v204
	v_exp_f32_e32 v220, v84
	v_cvt_pk_bf16_f32 v84, v213, v214
	v_cvt_pk_bf16_f32 v85, v215, v216
	v_cvt_pk_bf16_f32 v86, v217, v218
	v_cvt_pk_bf16_f32 v87, v219, v220
	s_nop 1
	v_mfma_f32_32x32x16_bf16 v[16:31], v[80:83], v[84:87], v[16:31]
	v_sub_f32_e32 v80, v94, v205
	v_exp_f32_e32 v94, v80
	ds_read2_b64 v[80:83], v185 offset0:8 offset1:10
	v_mfma_f32_32x32x16_bf16 v[0:15], v[88:91], v[84:87], v[0:15]
	ds_read2_b64 v[88:91], v187 offset0:40 offset1:42
	v_cvt_pk_bf16_f32 v84, v224, v225
	v_exp_f32_e32 v224, v64
	v_sub_f32_e32 v64, v68, v204
	v_exp_f32_e32 v225, v64
	v_sub_f32_e32 v64, v69, v204
	v_cvt_pk_bf16_f32 v85, v184, v226
	v_exp_f32_e32 v226, v64
	v_sub_f32_e32 v64, v70, v204
	v_cvt_pk_bf16_f32 v86, v227, v228
	v_exp_f32_e32 v227, v64
	v_sub_f32_e32 v64, v71, v204
	v_exp_f32_e32 v228, v64
	v_cvt_pk_bf16_f32 v87, v229, v230
	v_sub_f32_e32 v68, v95, v205
	v_cvt_pk_bf16_f32 v64, v221, v222
	s_waitcnt lgkmcnt(1)
; #define LAS __attribute__((address_space(3)))
; __device__ __forceinline__ unsigned pk2(float lo, float hi) { f32x2_t v = {lo, hi}; bf16x2_t b = __builtin_convertvector(v, bf16x2_t); return __builtin_bit_cast(unsigned, b); }
; template <int DK, bool IS_A>
; __device__ __forceinline__ void attn_unit(const Params& P, int l, LAS unsigned char* lds, int b, int grp, int qtok0, int nkeys) {
;     ...
;             __builtin_amdgcn_s_setprio(1);
; #pragma unroll
;             for (int i = 0; i < DK / 16; ++i)
; #pragma unroll
;                 for (int jj = 0; jj < 2; ++jj) {
;                     const bf16x8 kf = *(const LAS bf16x8*)(kb + jj * 32 * AK_PITCH + i * 32);
;                     pa[jj] = __builtin_amdgcn_mfma_f32_32x32x16_bf16(kf, qa[i], pa[jj], 0, 0, 0);
;                     pb[jj] = __builtin_amdgcn_mfma_f32_32x32x16_bf16(kf, qb[i], pb[jj], 0, 0, 0);
;                 }
;             __builtin_amdgcn_s_setprio(0);
;     ...
;             for (int ks = 0; ks < 4; ++ks) {
;                 const int o8 = 8 * (ks & 1);
;                 u32x4 w; const f32x16& xa = pa[ks >> 1]; const f32x16& xb = pb[ks >> 1];
;                 w.x = pk2(xa[o8], xa[o8 + 1]); w.y = pk2(xa[o8 + 2], xa[o8 + 3]); w.z = pk2(xa[o8 + 4], xa[o8 + 5]); w.w = pk2(xa[o8 + 6], xa[o8 + 7]);
;                 const bf16x8 pfa = __builtin_bit_cast(bf16x8, w);
;                 w.x = pk2(xb[o8], xb[o8 + 1]); w.y = pk2(xb[o8 + 2], xb[o8 + 3]); w.z = pk2(xb[o8 + 4], xb[o8 + 5]); w.w = pk2(xb[o8 + 6], xb[o8 + 7]);
;                 const bf16x8 pfb = __builtin_bit_cast(bf16x8, w);
;                 const u32x2 a0 = *(const LAS u32x2*)(vb + ks * 32), a1 = *(const LAS u32x2*)(vb + ks * 32 + 16);
;                 const u32x2 c0 = *(const LAS u32x2*)(vb + 32 * AV_PITCH + ks * 32), c1 = *(const LAS u32x2*)(vb + 32 * AV_PITCH + ks * 32 + 16);
;                 const bf16x8 v0 = __builtin_bit_cast(bf16x8, ((u32x4){a0.x, a0.y, a1.x, a1.y})), v1 = __builtin_bit_cast(bf16x8, ((u32x4){c0.x, c0.y, c1.x, c1.y}));
;                 oa0 = __builtin_amdgcn_mfma_f32_32x32x16_bf16(v0, pfa, oa0, 0, 0, 0);
;                 oa1 = __builtin_amdgcn_mfma_f32_32x32x16_bf16(v1, pfa, oa1, 0, 0, 0);
;                 ob0 = __builtin_amdgcn_mfma_f32_32x32x16_bf16(v0, pfb, ob0, 0, 0, 0);
;                 ob1 = __builtin_amdgcn_mfma_f32_32x32x16_bf16(v1, pfb, ob1, 0, 0, 0);
;             }
	v_mfma_f32_32x32x16_bf16 v[48:63], v[80:83], v[84:87], v[48:63]
	v_cvt_pk_bf16_f32 v65, v223, v224
	v_cvt_pk_bf16_f32 v66, v225, v226
	v_cvt_pk_bf16_f32 v67, v227, v228
	s_waitcnt lgkmcnt(0)
	v_mfma_f32_32x32x16_bf16 v[32:47], v[88:91], v[84:87], v[32:47]
	v_exp_f32_e32 v84, v68
	v_sub_f32_e32 v68, v72, v204
	v_exp_f32_e32 v229, v68
	v_sub_f32_e32 v68, v73, v204
	v_exp_f32_e32 v230, v68
	ds_read2_b64 v[68:71], v185 offset0:12 offset1:14
	v_sub_f32_e32 v72, v75, v204
	v_mfma_f32_32x32x16_bf16 v[16:31], v[80:83], v[64:67], v[16:31]
	ds_read2_b64 v[80:83], v187 offset0:44 offset1:46
	v_exp_f32_e32 v235, v72
	v_sub_f32_e32 v72, v76, v204
	v_exp_f32_e32 v236, v72
	v_sub_f32_e32 v72, v77, v204
	v_mfma_f32_32x32x16_bf16 v[0:15], v[88:91], v[64:67], v[0:15]
	v_sub_f32_e32 v64, v74, v204
	v_exp_f32_e32 v232, v64
	v_cvt_pk_bf16_f32 v64, v231, v233
	v_cvt_pk_bf16_f32 v65, v238, v239
	v_cvt_pk_bf16_f32 v66, v92, v93
	v_cvt_pk_bf16_f32 v67, v94, v84
	v_exp_f32_e32 v231, v72
	v_sub_f32_e32 v72, v78, v204
	s_waitcnt lgkmcnt(1)
	v_mfma_f32_32x32x16_bf16 v[48:63], v[68:71], v[64:67], v[48:63]
	v_exp_f32_e32 v233, v72
	s_waitcnt lgkmcnt(0)
	v_mfma_f32_32x32x16_bf16 v[32:47], v[80:83], v[64:67], v[32:47]
	v_sub_f32_e32 v64, v79, v204
	v_exp_f32_e32 v234, v64
	v_cvt_pk_bf16_f32 v64, v229, v230
	v_cvt_pk_bf16_f32 v65, v232, v235
	v_cvt_pk_bf16_f32 v66, v236, v231
	v_cvt_pk_bf16_f32 v67, v233, v234
	s_nop 1
	v_mfma_f32_32x32x16_bf16 v[16:31], v[68:71], v[64:67], v[16:31]
	v_add_f32_e32 v68, v238, v237
	v_add_f32_e32 v68, v239, v68
	v_add_f32_e32 v68, v92, v68
	v_add_f32_e32 v68, v93, v68
	v_add_f32_e32 v68, v94, v68
	v_add_f32_e32 v68, v84, v68
	v_add_f32_e32 v198, v198, v68
	v_mfma_f32_32x32x16_bf16 v[0:15], v[80:83], v[64:67], v[0:15]
	ds_read_b128 v[64:67], v199 offset:9216
	ds_read_b128 v[238:241], v199 offset:9248
	s_waitcnt lgkmcnt(1)
	v_mfma_f32_32x32x16_bf16 v[112:127], v[64:67], v[142:145], 0
	v_mfma_f32_32x32x16_bf16 v[96:111], v[64:67], v[146:149], 0
	ds_read_b128 v[64:67], v199 offset:13824
	s_waitcnt lgkmcnt(1)
	v_mfma_f32_32x32x16_bf16 v[112:127], v[238:241], v[154:157], v[112:127]
	v_mfma_f32_32x32x16_bf16 v[96:111], v[238:241], v[162:165], v[96:111]
	ds_read_b128 v[238:241], v199 offset:13856
	s_waitcnt lgkmcnt(1)
	v_mfma_f32_32x32x16_bf16 v[80:95], v[64:67], v[142:145], 0
	v_mfma_f32_32x32x16_bf16 v[64:79], v[64:67], v[146:149], 0
	s_waitcnt lgkmcnt(0)
	v_mfma_f32_32x32x16_bf16 v[80:95], v[238:241], v[154:157], v[80:95]
	v_mfma_f32_32x32x16_bf16 v[64:79], v[238:241], v[162:165], v[64:79]
	ds_read_b128 v[238:241], v199 offset:9280
	s_waitcnt lgkmcnt(0)
	v_mfma_f32_32x32x16_bf16 v[112:127], v[238:241], v[158:161], v[112:127]
	v_mfma_f32_32x32x16_bf16 v[96:111], v[238:241], v[170:173], v[96:111]
	ds_read_b128 v[238:241], v199 offset:13888
	s_waitcnt lgkmcnt(0)
	v_mfma_f32_32x32x16_bf16 v[80:95], v[238:241], v[158:161], v[80:95]
	v_mfma_f32_32x32x16_bf16 v[64:79], v[238:241], v[170:173], v[64:79]
	ds_read_b128 v[238:241], v199 offset:9312
	s_waitcnt lgkmcnt(0)
	v_mfma_f32_32x32x16_bf16 v[112:127], v[238:241], v[166:169], v[112:127]
	v_mfma_f32_32x32x16_bf16 v[96:111], v[238:241], v[174:177], v[96:111]
	ds_read_b128 v[238:241], v199 offset:13920
	s_waitcnt lgkmcnt(0)
	v_mfma_f32_32x32x16_bf16 v[80:95], v[238:241], v[166:169], v[80:95]
	v_mfma_f32_32x32x16_bf16 v[64:79], v[238:241], v[174:177], v[64:79]
	s_nop 9
	v_max_f32_e32 v184, v80, v80
	v_max_f32_e32 v199, v112, v112
	v_max_f32_e32 v184, v199, v184
	v_max3_f32 v199, v81, v114, v82
	v_max3_f32 v184, v184, v113, v115
	v_max3_f32 v199, v199, v116, v84
	v_max3_f32 v184, v184, v83, v117
	v_max3_f32 v199, v199, v118, v86
	v_max3_f32 v184, v184, v85, v119
	v_max3_f32 v199, v199, v120, v88
	v_max3_f32 v184, v184, v87, v121
	v_max3_f32 v199, v199, v122, v90
	v_max3_f32 v184, v184, v89, v123
	v_max3_f32 v199, v199, v124, v92
	v_max3_f32 v184, v184, v91, v125
	v_max3_f32 v199, v199, v126, v94
	v_max3_f32 v184, v184, v93, v127
	v_max3_f32 v184, v184, v95, v199
	ds_bpermute_b32 v199, v181, v184
	s_waitcnt lgkmcnt(0)
	v_max3_f32 v184, v205, v184, v199
	v_cmp_gt_f32_e32 vcc, v184, v205
	s_cbranch_vccz .LBB0_453
	v_sub_f32_e32 v199, v205, v184
	v_exp_f32_e32 v238, v199
	s_nop 0
	v_pk_mul_f32 v[62:63], v[62:63], v[238:239] op_sel_hi:[1,0]
	v_pk_mul_f32 v[60:61], v[60:61], v[238:239] op_sel_hi:[1,0]
	v_pk_mul_f32 v[58:59], v[58:59], v[238:239] op_sel_hi:[1,0]
	v_pk_mul_f32 v[56:57], v[56:57], v[238:239] op_sel_hi:[1,0]
	v_pk_mul_f32 v[54:55], v[54:55], v[238:239] op_sel_hi:[1,0]
	v_pk_mul_f32 v[52:53], v[52:53], v[238:239] op_sel_hi:[1,0]
	v_pk_mul_f32 v[50:51], v[50:51], v[238:239] op_sel_hi:[1,0]
	v_pk_mul_f32 v[48:49], v[48:49], v[238:239] op_sel_hi:[1,0]
	v_pk_mul_f32 v[46:47], v[46:47], v[238:239] op_sel_hi:[1,0]
	v_pk_mul_f32 v[44:45], v[44:45], v[238:239] op_sel_hi:[1,0]
	v_pk_mul_f32 v[42:43], v[42:43], v[238:239] op_sel_hi:[1,0]
	v_pk_mul_f32 v[40:41], v[40:41], v[238:239] op_sel_hi:[1,0]
	v_pk_mul_f32 v[38:39], v[38:39], v[238:239] op_sel_hi:[1,0]
	v_pk_mul_f32 v[36:37], v[36:37], v[238:239] op_sel_hi:[1,0]
	v_pk_mul_f32 v[34:35], v[34:35], v[238:239] op_sel_hi:[1,0]
	v_pk_mul_f32 v[32:33], v[32:33], v[238:239] op_sel_hi:[1,0]
	v_mul_f32_e32 v198, v198, v238
	s_branch .LBB0_454

; #define LAS __attribute__((address_space(3)))
; __device__ __forceinline__ float shx(float v, int o, int lane) { return __builtin_bit_cast(float, __builtin_amdgcn_ds_bpermute((lane ^ o) << 2, __builtin_bit_cast(int, v))); }
; template <int DK, bool IS_A>
; __device__ __forceinline__ void attn_unit(const Params& P, int l, LAS unsigned char* lds, int b, int grp, int qtok0, int nkeys) {
;     ...
;     la += shx(la, 32, lane); lb_ += shx(lb_, 32, lane);
;     { const float ia = 1.0f / la, ib = 1.0f / lb_;
; #pragma unroll
;       for (int r = 0; r < 16; ++r) { oa0[r] *= ia; oa1[r] *= ia; ob0[r] *= ib; ob1[r] *= ib; } }
;     ...
;     if (IS_A) {
;         LAS float* X = (LAS float*)lds;
;         if (s == 1) {
; #pragma unroll
;             for (int r = 0; r < 16; ++r) { X[(wq * 64 + r) * 64 + lane] = oa0[r]; X[(wq * 64 + 16 + r) * 64 + lane] = oa1[r]; X[(wq * 64 + 32 + r) * 64 + lane] = ob0[r]; X[(wq * 64 + 48 + r) * 64 + lane] = ob1[r]; }
;         }
;         __syncthreads();
;         if (s == 0) {
;             const float lam = ((const float*)(P.ws + WS_CTL))[CW_LAM + l];
;             const float oml_init = ((const float*)(P.ws + WS_CTL))[CW_LAM + 8 + l];
;             const float* gn = P.diff_norm + (size_t)l * 64;
;             float sa = 0.f, sb = 0.f;
; #pragma unroll
;             for (int r = 0; r < 16; ++r) {
;                 oa0[r] -= lam * X[(wq * 64 + r) * 64 + lane]; oa1[r] -= lam * X[(wq * 64 + 16 + r) * 64 + lane]; sa += oa0[r] * oa0[r] + oa1[r] * oa1[r];
;                 ob0[r] -= lam * X[(wq * 64 + 32 + r) * 64 + lane]; ob1[r] -= lam * X[(wq * 64 + 48 + r) * 64 + lane]; sb += ob0[r] * ob0[r] + ob1[r] * ob1[r]; }
;             sa += shx(sa, 32, lane); sb += shx(sb, 32, lane);
;             { const float rs_ = (1.0f / sqrtf(sa * (1.0f / 64.0f) + RMS_EPS)) * oml_init; AT_OUT(oa0, oa1, qrow, grp * 64, true); }
;             { const float rs_ = (1.0f / sqrtf(sb * (1.0f / 64.0f) + RMS_EPS)) * oml_init; AT_OUT(ob0, ob1, qrow + 32, grp * 64, true); }
;         }
;         __syncthreads();
;     } else {
;         const float* gn = nullptr; const float rs_ = 1.f;
;         AT_OUT(oa0, oa1, qrow, 512 + (2 * grp + s) * 64, false);
;         AT_OUT(ob0, ob1, qrow + 32, 512 + (2 * grp + s) * 64, false);
.LBB0_459:
	s_setprio 0
	ds_bpermute_b32 v64, v181, v198
	ds_bpermute_b32 v65, v181, v183
	v_mov_b32_e32 v187, v129
	s_waitcnt lgkmcnt(1)
	v_add_f32_e32 v64, v198, v64
	v_div_scale_f32 v66, s[8:9], v64, v64, 1.0
	v_rcp_f32_e32 v67, v66
	s_waitcnt lgkmcnt(0)
	v_add_f32_e32 v65, v183, v65
	v_fma_f32 v68, -v66, v67, 1.0
	v_fmac_f32_e32 v67, v68, v67
	v_div_scale_f32 v68, vcc, 1.0, v64, 1.0
	v_mul_f32_e32 v69, v68, v67
	v_fma_f32 v70, -v66, v69, v68
	v_fmac_f32_e32 v69, v70, v67
	v_fma_f32 v66, -v66, v69, v68
	v_div_fmas_f32 v66, v66, v67, v69
	v_div_fixup_f32 v64, v66, v64, 1.0
	v_div_scale_f32 v66, s[8:9], v65, v65, 1.0
	v_rcp_f32_e32 v67, v66
	v_readlane_b32 s8, v255, 6
	v_pk_mul_f32 v[48:49], v[48:49], v[64:65] op_sel_hi:[1,0]
	v_pk_mul_f32 v[32:33], v[32:33], v[64:65] op_sel_hi:[1,0]
	v_fma_f32 v68, -v66, v67, 1.0
	v_fmac_f32_e32 v67, v68, v67
	v_div_scale_f32 v68, vcc, 1.0, v65, 1.0
	v_mul_f32_e32 v69, v68, v67
	v_fma_f32 v70, -v66, v69, v68
	v_fmac_f32_e32 v69, v70, v67
	v_fma_f32 v66, -v66, v69, v68
	v_div_fmas_f32 v66, v66, v67, v69
	v_div_fixup_f32 v66, v66, v65, 1.0
	v_pk_mul_f32 v[50:51], v[50:51], v[64:65] op_sel_hi:[1,0]
	v_pk_mul_f32 v[34:35], v[34:35], v[64:65] op_sel_hi:[1,0]
	v_pk_mul_f32 v[52:53], v[52:53], v[64:65] op_sel_hi:[1,0]
	v_pk_mul_f32 v[36:37], v[36:37], v[64:65] op_sel_hi:[1,0]
	v_pk_mul_f32 v[54:55], v[54:55], v[64:65] op_sel_hi:[1,0]
	v_pk_mul_f32 v[38:39], v[38:39], v[64:65] op_sel_hi:[1,0]
	v_pk_mul_f32 v[56:57], v[56:57], v[64:65] op_sel_hi:[1,0]
	v_pk_mul_f32 v[40:41], v[40:41], v[64:65] op_sel_hi:[1,0]
	v_pk_mul_f32 v[58:59], v[58:59], v[64:65] op_sel_hi:[1,0]
	v_pk_mul_f32 v[42:43], v[42:43], v[64:65] op_sel_hi:[1,0]
	v_pk_mul_f32 v[60:61], v[60:61], v[64:65] op_sel_hi:[1,0]
	v_pk_mul_f32 v[44:45], v[44:45], v[64:65] op_sel_hi:[1,0]
	v_pk_mul_f32 v[62:63], v[62:63], v[64:65] op_sel_hi:[1,0]
	v_pk_mul_f32 v[46:47], v[46:47], v[64:65] op_sel_hi:[1,0]
	v_lshlrev_b64 v[64:65], 11, v[128:129]
	v_readlane_b32 s9, v255, 7
	v_pk_mul_f32 v[16:17], v[16:17], v[66:67] op_sel_hi:[1,0]
	v_pk_mul_f32 v[0:1], v[0:1], v[66:67] op_sel_hi:[1,0]
	v_pk_mul_f32 v[18:19], v[18:19], v[66:67] op_sel_hi:[1,0]
	v_pk_mul_f32 v[2:3], v[2:3], v[66:67] op_sel_hi:[1,0]
	v_pk_mul_f32 v[20:21], v[20:21], v[66:67] op_sel_hi:[1,0]
	v_pk_mul_f32 v[4:5], v[4:5], v[66:67] op_sel_hi:[1,0]
	v_pk_mul_f32 v[22:23], v[22:23], v[66:67] op_sel_hi:[1,0]
	v_pk_mul_f32 v[6:7], v[6:7], v[66:67] op_sel_hi:[1,0]
	v_pk_mul_f32 v[24:25], v[24:25], v[66:67] op_sel_hi:[1,0]
	v_pk_mul_f32 v[8:9], v[8:9], v[66:67] op_sel_hi:[1,0]
	v_pk_mul_f32 v[26:27], v[26:27], v[66:67] op_sel_hi:[1,0]
	v_pk_mul_f32 v[10:11], v[10:11], v[66:67] op_sel_hi:[1,0]
	v_pk_mul_f32 v[28:29], v[28:29], v[66:67] op_sel_hi:[1,0]
	v_pk_mul_f32 v[12:13], v[12:13], v[66:67] op_sel_hi:[1,0]
	v_pk_mul_f32 v[30:31], v[30:31], v[66:67] op_sel_hi:[1,0]
	v_pk_mul_f32 v[14:15], v[14:15], v[66:67] op_sel_hi:[1,0]
	v_lshl_add_u64 v[64:65], s[8:9], 0, v[64:65]
	v_lshlrev_b64 v[66:67], 1, v[188:189]
	s_mov_b64 s[8:9], 0x400
	v_lshl_add_u64 v[68:69], v[66:67], 0, s[8:9]
	v_lshl_add_u64 v[66:67], v[64:65], 0, v[66:67]
	v_cvt_pk_bf16_f32 v48, v48, v49
	v_cvt_pk_bf16_f32 v49, v50, v51
	v_lshl_add_u64 v[50:51], v[66:67], 0, v[186:187]
	v_cvt_pk_bf16_f32 v32, v32, v33
	v_cvt_pk_bf16_f32 v33, v34, v35
	global_store_dwordx2 v[50:51], v[32:33], off offset:1088
	v_cvt_pk_bf16_f32 v32, v36, v37
	v_cvt_pk_bf16_f32 v33, v38, v39
	global_store_dwordx2 v[50:51], v[32:33], off offset:1104
	v_cvt_pk_bf16_f32 v32, v40, v41
	v_cvt_pk_bf16_f32 v33, v42, v43
	global_store_dwordx2 v[50:51], v[32:33], off offset:1120
	v_cvt_pk_bf16_f32 v32, v44, v45
	v_cvt_pk_bf16_f32 v33, v46, v47
	s_mov_b64 s[8:9], 0x10000
	global_store_dwordx2 v[50:51], v[32:33], off offset:1136
	v_lshl_add_u64 v[32:33], v[64:65], 0, s[8:9]
	v_cvt_pk_bf16_f32 v16, v16, v17
	v_cvt_pk_bf16_f32 v17, v18, v19
	v_lshl_add_u64 v[18:19], v[32:33], 0, v[186:187]
	v_lshl_add_u64 v[34:35], v[32:33], 0, v[68:69]
	v_lshl_add_u64 v[18:19], v[18:19], 0, v[68:69]
	global_store_dwordx2 v[18:19], v[16:17], off
	v_lshl_add_u64 v[18:19], v[34:35], 0, v[186:187]
	v_cvt_pk_bf16_f32 v0, v0, v1
	v_cvt_pk_bf16_f32 v1, v2, v3
	global_store_dwordx2 v[50:51], v[48:49], off offset:1024
	v_cvt_pk_bf16_f32 v48, v52, v53
	v_cvt_pk_bf16_f32 v49, v54, v55
	v_cvt_pk_bf16_f32 v16, v20, v21
	v_cvt_pk_bf16_f32 v17, v22, v23
	global_store_dwordx2 v[18:19], v[0:1], off offset:64
	v_cvt_pk_bf16_f32 v0, v4, v5
	v_cvt_pk_bf16_f32 v1, v6, v7
	global_store_dwordx2 v[50:51], v[48:49], off offset:1040
	v_cvt_pk_bf16_f32 v48, v56, v57
	v_cvt_pk_bf16_f32 v49, v58, v59
	global_store_dwordx2 v[18:19], v[16:17], off offset:16
	v_cvt_pk_bf16_f32 v16, v24, v25
	v_cvt_pk_bf16_f32 v17, v26, v27
	global_store_dwordx2 v[18:19], v[0:1], off offset:80
	v_cvt_pk_bf16_f32 v0, v8, v9
	v_cvt_pk_bf16_f32 v1, v10, v11
	global_store_dwordx2 v[50:51], v[48:49], off offset:1056
	v_cvt_pk_bf16_f32 v48, v60, v61
	v_cvt_pk_bf16_f32 v49, v62, v63
	global_store_dwordx2 v[18:19], v[16:17], off offset:32
	v_cvt_pk_bf16_f32 v16, v28, v29
	v_cvt_pk_bf16_f32 v17, v30, v31
	global_store_dwordx2 v[18:19], v[0:1], off offset:96
	v_cvt_pk_bf16_f32 v0, v12, v13
	v_cvt_pk_bf16_f32 v1, v14, v15
	global_store_dwordx2 v[50:51], v[48:49], off offset:1072
	global_store_dwordx2 v[18:19], v[16:17], off offset:48
	global_store_dwordx2 v[18:19], v[0:1], off offset:112
